# GLA and HGRN2 stream loops: gate-value register rotation moved to the chunk start, staging waits counted so loads keep a two-chunk lead (on top of attention prefetch)
# baseline (speedup 1.0000x reference)
.LBB0_961:
	s_or_b64 exec, exec, s[10:11]
	v_add_u32_e32 v101, 0x200, v150
	v_ashrrev_i32_e32 v152, 4, v150
	v_ashrrev_i32_e32 v94, 4, v101
	s_lshl_b32 s24, s2, 13
	s_mov_b32 s25, s28
	v_ashrrev_i32_e32 v153, 31, v152
	v_lshlrev_b32_e32 v38, 3, v148
	v_ashrrev_i32_e32 v95, 31, v94
	v_lshl_add_u64 v[36:37], s[24:25], 0, v[152:153]
	s_lshl_b32 s2, s93, 23
	v_and_b32_e32 v180, 0x78, v38
	v_lshl_add_u64 v[38:39], s[24:25], 0, v[94:95]
	v_lshlrev_b64 v[88:89], 9, v[36:37]
	s_and_b32 s2, s2, 0x1000000
	v_lshlrev_b64 v[90:91], 9, v[38:39]
	v_add_u32_e32 v78, s8, v84
	v_lshl_add_u64 v[36:37], s[60:61], 0, v[88:89]
	s_and_b32 s9, s9, 0x80
	s_or_b32 s10, s2, 0xa000000
	s_mov_b32 s11, s28
	v_lshl_add_u64 v[38:39], s[60:61], 0, v[90:91]
	v_add_u32_e32 v85, s12, v78
	v_lshl_add_u64 v[36:37], v[36:37], 0, s[10:11]
	s_lshl_b32 s12, s9, 1
	s_mov_b32 s13, s28
	v_lshl_add_u64 v[38:39], v[38:39], 0, s[10:11]
	v_lshl_add_u64 v[36:37], v[36:37], 0, s[12:13]
	v_lshlrev_b32_e32 v154, 1, v180
	v_mov_b32_e32 v155, v181
	v_lshl_add_u64 v[38:39], v[38:39], 0, s[12:13]
	v_add_u32_e32 v40, 0xc00, v85
	v_and_b32_e32 v86, 15, v148
	v_lshl_add_u64 v[36:37], v[36:37], 0, v[154:155]
	v_lshl_add_u64 v[38:39], v[38:39], 0, v[154:155]
	global_load_dwordx4 v[48:51], v[36:37], off
	global_load_dwordx4 v[52:55], v[38:39], off
	v_or_b32_e32 v36, s24, v86
	v_mov_b32_e32 v37, v181
	v_ashrrev_i32_e32 v38, 8, v40
	v_lshlrev_b64 v[36:37], 9, v[36:37]
	v_ashrrev_i32_e32 v39, 31, v38
	v_lshl_add_u64 v[36:37], s[60:61], 0, v[36:37]
	v_and_b32_e32 v40, 0xfc, v85
	v_lshlrev_b64 v[92:93], 24, v[38:39]
	v_lshl_add_u64 v[96:97], v[36:37], 0, v[92:93]
	v_lshlrev_b32_e32 v98, 1, v40
	v_mov_b32_e32 v99, v181
	v_lshl_add_u64 v[36:37], v[96:97], 0, v[98:99]
	v_add_co_u32_e32 v38, vcc, s5, v36
	v_mov_b32_e32 v87, v181
	s_nop 0
	v_addc_co_u32_e32 v39, vcc, 0, v37, vcc
	v_add_co_u32_e32 v40, vcc, s3, v36
	s_mov_b32 s3, 0x10000
	s_nop 0
	v_addc_co_u32_e32 v41, vcc, 0, v37, vcc
	v_add_co_u32_e32 v42, vcc, s4, v36
	v_mov_b32_e32 v203, v181
	s_nop 0
	v_addc_co_u32_e32 v43, vcc, 0, v37, vcc
	global_load_dwordx2 v[178:179], v[36:37], off
	global_load_dwordx2 v[182:183], v[38:39], off
	global_load_dwordx2 v[184:185], v[40:41], off
	global_load_dwordx2 v[186:187], v[42:43], off
	v_add_co_u32_e32 v36, vcc, s3, v68
	s_mov_b32 s3, 0x14000
	s_nop 0
	v_addc_co_u32_e32 v37, vcc, 0, v69, vcc
	v_add_co_u32_e32 v40, vcc, s3, v68
	s_mov_b32 s3, 0x18000
	s_nop 0
	v_addc_co_u32_e32 v41, vcc, 0, v69, vcc
	v_add_co_u32_e32 v44, vcc, s3, v68
	s_mov_b32 s3, 0x1c000
	s_nop 0
	v_addc_co_u32_e32 v45, vcc, 0, v69, vcc
	v_add_co_u32_e32 v56, vcc, s3, v68
	s_mov_b32 s3, 0x12000
	s_nop 0
	v_addc_co_u32_e32 v57, vcc, 0, v69, vcc
	v_add_co_u32_e32 v60, vcc, s3, v68
	s_mov_b32 s3, 0x16000
	s_nop 0
	v_addc_co_u32_e32 v61, vcc, 0, v69, vcc
	v_add_co_u32_e32 v64, vcc, s3, v68
	global_load_dwordx4 v[36:39], v[36:37], off offset:512
	s_nop 0
	global_load_dwordx4 v[40:43], v[40:41], off offset:512
	v_addc_co_u32_e32 v65, vcc, 0, v69, vcc
	v_add_co_u32_e32 v70, vcc, 0x1a000, v68
	global_load_dwordx4 v[44:47], v[44:45], off offset:512
	s_nop 0
	global_load_dwordx4 v[56:59], v[56:57], off offset:512
	v_addc_co_u32_e32 v71, vcc, 0, v69, vcc
	v_add_co_u32_e32 v72, vcc, 0x1e000, v68
	global_load_dwordx4 v[60:63], v[60:61], off offset:512
	s_nop 0
	global_load_dwordx4 v[64:67], v[64:65], off offset:512
	v_addc_co_u32_e32 v73, vcc, 0, v69, vcc
	global_load_dwordx4 v[68:71], v[70:71], off offset:512
	s_nop 0
	global_load_dwordx4 v[72:75], v[72:73], off offset:512
	s_movk_i32 s3, 0x200
	s_and_saveexec_b64 s[14:15], s[6:7]
	s_cbranch_execz .LBB0_963
	v_add_co_u32_e32 v76, vcc, 0x20000, v76
	s_nop 1
	v_addc_co_u32_e32 v77, vcc, 0, v77, vcc
	global_load_dword v203, v[76:77], off offset:512

.LBB0_964:
	s_or_b64 exec, exec, s[22:23]
	s_waitcnt lgkmcnt(0)
	s_barrier
	ds_read_b128 v[132:135], v216
	ds_read_b128 v[136:139], v216 offset:16
	v_subrev_u32_e32 v154, 48, v170
	v_mov_b32_e32 v171, v155
	s_add_i32 s2, s2, 2
	s_waitcnt lgkmcnt(1)
	v_mov_b32_e32 v140, v132
	s_waitcnt lgkmcnt(0)
	v_mov_b32_e32 v141, v136
	v_mov_b32_e32 v136, v133
	v_pk_add_f32 v[132:133], v[140:141], v[136:137]
	v_mov_b32_e32 v136, v134
	v_mov_b32_e32 v137, v138
	v_mov_b32_e32 v138, v135
	v_pk_add_f32 v[134:135], v[136:137], v[138:139]
	v_lshl_add_u64 v[160:161], v[160:161], 0, s[36:37]
	v_pk_add_f32 v[132:133], v[132:133], v[134:135]
	v_lshlrev_b32_e32 v134, 16, v195
	v_add_f32_e32 v132, v132, v133
	v_fmamk_f32 v132, v132, 0x3c000000, v151
	v_rsq_f32_e32 v132, v132
	v_and_b32_e32 v135, 0xffff0000, v195
	v_mul_f32_e32 v138, 0xbfb8aa3b, v134
	v_mul_f32_e32 v139, 0xbfb8aa3b, v135
	v_pk_mul_f32 v[130:131], v[130:131], v[132:133] op_sel_hi:[1,0]
	v_pk_mul_f32 v[128:129], v[128:129], v[132:133] op_sel_hi:[1,0]
	v_pk_mul_f32 v[136:137], v[2:3], v[130:131]
	v_lshlrev_b32_e32 v130, 16, v194
	v_and_b32_e32 v131, 0xffff0000, v194
	v_mul_f32_e32 v132, 0xbfb8aa3b, v130
	v_mul_f32_e32 v133, 0xbfb8aa3b, v131
	v_exp_f32_e32 v132, v132
	v_exp_f32_e32 v133, v133
	v_exp_f32_e32 v138, v138
	v_exp_f32_e32 v139, v139
	v_add_f32_e32 v132, 1.0, v132
	v_add_f32_e32 v133, 1.0, v133
	v_rcp_f32_e32 v132, v132
	v_rcp_f32_e32 v133, v133
	v_add_f32_e32 v138, 1.0, v138
	v_add_f32_e32 v139, 1.0, v139
	v_rcp_f32_e32 v138, v138
	v_rcp_f32_e32 v139, v139
	v_pk_mul_f32 v[128:129], v[0:1], v[128:129]
	v_pk_mul_f32 v[130:131], v[132:133], v[130:131]
	v_lshl_add_u64 v[162:163], v[162:163], 0, s[36:37]
	v_pk_mul_f32 v[128:129], v[130:131], v[128:129]
	v_pk_mul_f32 v[138:139], v[138:139], v[134:135]
	v_cvt_pk_bf16_f32 v140, v128, v129
	ds_read_b128 v[128:131], v216 offset:512
	ds_read_b128 v[132:135], v216 offset:528
	v_pk_mul_f32 v[136:137], v[138:139], v[136:137]
	v_lshl_add_u64 v[164:165], v[164:165], 0, s[36:37]
	v_cvt_pk_bf16_f32 v141, v136, v137
	s_waitcnt lgkmcnt(1)
	v_mov_b32_e32 v136, v128
	s_waitcnt lgkmcnt(0)
	v_mov_b32_e32 v137, v132
	v_mov_b32_e32 v132, v129
	v_pk_add_f32 v[128:129], v[136:137], v[132:133]
	v_mov_b32_e32 v132, v130
	v_mov_b32_e32 v133, v134
	v_mov_b32_e32 v134, v131
	v_pk_add_f32 v[130:131], v[132:133], v[134:135]
	v_lshl_add_u64 v[166:167], v[166:167], 0, s[38:39]
	v_pk_add_f32 v[128:129], v[128:129], v[130:131]
	v_lshlrev_b64 v[130:131], 7, v[154:155]
	v_add_f32_e32 v128, v128, v129
	v_fmamk_f32 v128, v128, 0x3c000000, v151
	v_rsq_f32_e32 v128, v128
	v_lshl_add_u64 v[130:131], v[158:159], 0, v[130:131]
	global_store_dwordx2 v[130:131], v[140:141], off
	v_lshlrev_b32_e32 v130, 16, v193
	v_pk_mul_f32 v[126:127], v[126:127], v[128:129] op_sel_hi:[1,0]
	v_pk_mul_f32 v[124:125], v[124:125], v[128:129] op_sel_hi:[1,0]
	v_pk_mul_f32 v[132:133], v[2:3], v[126:127]
	v_lshlrev_b32_e32 v126, 16, v192
	v_and_b32_e32 v127, 0xffff0000, v192
	v_mul_f32_e32 v128, 0xbfb8aa3b, v126
	v_mul_f32_e32 v129, 0xbfb8aa3b, v127
	v_exp_f32_e32 v128, v128
	v_exp_f32_e32 v129, v129
	v_and_b32_e32 v131, 0xffff0000, v193
	v_mul_f32_e32 v134, 0xbfb8aa3b, v130
	v_mul_f32_e32 v135, 0xbfb8aa3b, v131
	v_exp_f32_e32 v134, v134
	v_exp_f32_e32 v135, v135
	v_add_f32_e32 v128, 1.0, v128
	v_add_f32_e32 v129, 1.0, v129
	v_rcp_f32_e32 v128, v128
	v_rcp_f32_e32 v129, v129
	v_add_f32_e32 v134, 1.0, v134
	v_add_f32_e32 v135, 1.0, v135
	v_rcp_f32_e32 v134, v134
	v_rcp_f32_e32 v135, v135
	v_pk_mul_f32 v[124:125], v[0:1], v[124:125]
	v_pk_mul_f32 v[126:127], v[128:129], v[126:127]
	v_subrev_u32_e32 v154, 32, v170
	v_pk_mul_f32 v[124:125], v[126:127], v[124:125]
	v_pk_mul_f32 v[134:135], v[134:135], v[130:131]
	v_cvt_pk_bf16_f32 v136, v124, v125
	ds_read_b128 v[124:127], v216 offset:1024
	ds_read_b128 v[128:131], v216 offset:1040
	v_pk_mul_f32 v[132:133], v[134:135], v[132:133]
	v_lshl_add_u64 v[168:169], v[168:169], 0, s[38:39]
	v_cvt_pk_bf16_f32 v137, v132, v133
	s_waitcnt lgkmcnt(1)
	v_mov_b32_e32 v132, v124
	s_waitcnt lgkmcnt(0)
	v_mov_b32_e32 v133, v128
	v_mov_b32_e32 v128, v125
	v_pk_add_f32 v[124:125], v[132:133], v[128:129]
	v_mov_b32_e32 v128, v126
	v_mov_b32_e32 v129, v130
	v_mov_b32_e32 v130, v127
	v_pk_add_f32 v[126:127], v[128:129], v[130:131]
	s_andn2_b64 vcc, exec, s[40:41]
	v_pk_add_f32 v[124:125], v[124:125], v[126:127]
	v_lshlrev_b64 v[126:127], 7, v[154:155]
	v_add_f32_e32 v124, v124, v125
	v_fmamk_f32 v124, v124, 0x3c000000, v151
	v_rsq_f32_e32 v124, v124
	v_lshl_add_u64 v[126:127], v[158:159], 0, v[126:127]
	global_store_dwordx2 v[126:127], v[136:137], off
	v_lshlrev_b32_e32 v126, 16, v191
	v_pk_mul_f32 v[122:123], v[122:123], v[124:125] op_sel_hi:[1,0]
	v_pk_mul_f32 v[120:121], v[120:121], v[124:125] op_sel_hi:[1,0]
	v_pk_mul_f32 v[128:129], v[2:3], v[122:123]
	v_lshlrev_b32_e32 v122, 16, v190
	v_and_b32_e32 v123, 0xffff0000, v190
	v_mul_f32_e32 v124, 0xbfb8aa3b, v122
	v_mul_f32_e32 v125, 0xbfb8aa3b, v123
	v_exp_f32_e32 v124, v124
	v_exp_f32_e32 v125, v125
	v_and_b32_e32 v127, 0xffff0000, v191
	v_mul_f32_e32 v130, 0xbfb8aa3b, v126
	v_mul_f32_e32 v131, 0xbfb8aa3b, v127
	v_exp_f32_e32 v130, v130
	v_exp_f32_e32 v131, v131
	v_add_f32_e32 v124, 1.0, v124
	v_add_f32_e32 v125, 1.0, v125
	v_rcp_f32_e32 v124, v124
	v_rcp_f32_e32 v125, v125
	v_add_f32_e32 v130, 1.0, v130
	v_add_f32_e32 v131, 1.0, v131
	v_rcp_f32_e32 v130, v130
	v_rcp_f32_e32 v131, v131
	v_pk_mul_f32 v[120:121], v[0:1], v[120:121]
	v_pk_mul_f32 v[122:123], v[124:125], v[122:123]
	v_add_u32_e32 v154, -16, v170
	v_pk_mul_f32 v[120:121], v[122:123], v[120:121]
	v_pk_mul_f32 v[130:131], v[130:131], v[126:127]
	v_cvt_pk_bf16_f32 v132, v120, v121
	ds_read_b128 v[120:123], v216 offset:1536
	ds_read_b128 v[124:127], v216 offset:1552
	v_pk_mul_f32 v[128:129], v[130:131], v[128:129]
	v_cvt_pk_bf16_f32 v133, v128, v129
	s_waitcnt lgkmcnt(1)
	v_mov_b32_e32 v128, v120
	s_waitcnt lgkmcnt(0)
	v_mov_b32_e32 v129, v124
	v_mov_b32_e32 v124, v121
	v_pk_add_f32 v[120:121], v[128:129], v[124:125]
	v_mov_b32_e32 v124, v122
	v_mov_b32_e32 v125, v126
	v_mov_b32_e32 v126, v123
	v_pk_add_f32 v[122:123], v[124:125], v[126:127]
	v_lshlrev_b32_e32 v124, 16, v189
	v_pk_add_f32 v[120:121], v[120:121], v[122:123]
	v_lshlrev_b64 v[122:123], 7, v[154:155]
	v_add_f32_e32 v120, v120, v121
	v_fmamk_f32 v120, v120, 0x3c000000, v151
	v_rsq_f32_e32 v120, v120
	v_lshl_add_u64 v[122:123], v[158:159], 0, v[122:123]
	global_store_dwordx2 v[122:123], v[132:133], off
	v_and_b32_e32 v125, 0xffff0000, v189
	v_pk_mul_f32 v[116:117], v[116:117], v[120:121] op_sel_hi:[1,0]
	v_pk_mul_f32 v[118:119], v[118:119], v[120:121] op_sel_hi:[1,0]
	v_lshlrev_b32_e32 v120, 16, v188
	v_and_b32_e32 v121, 0xffff0000, v188
	v_mul_f32_e32 v122, 0xbfb8aa3b, v120
	v_mul_f32_e32 v123, 0xbfb8aa3b, v121
	v_exp_f32_e32 v122, v122
	v_exp_f32_e32 v123, v123
	v_mul_f32_e32 v126, 0xbfb8aa3b, v124
	v_mul_f32_e32 v127, 0xbfb8aa3b, v125
	v_exp_f32_e32 v126, v126
	v_exp_f32_e32 v127, v127
	v_add_f32_e32 v122, 1.0, v122
	v_add_f32_e32 v123, 1.0, v123
	v_rcp_f32_e32 v122, v122
	v_rcp_f32_e32 v123, v123
	v_add_f32_e32 v126, 1.0, v126
	v_add_f32_e32 v127, 1.0, v127
	v_rcp_f32_e32 v126, v126
	v_rcp_f32_e32 v127, v127
	v_pk_mul_f32 v[116:117], v[0:1], v[116:117]
	v_pk_mul_f32 v[120:121], v[122:123], v[120:121]
	v_pk_mul_f32 v[118:119], v[2:3], v[118:119]
	v_pk_mul_f32 v[116:117], v[120:121], v[116:117]
	v_pk_mul_f32 v[120:121], v[126:127], v[124:125]
	v_cvt_pk_bf16_f32 v116, v116, v117
	v_pk_mul_f32 v[118:119], v[120:121], v[118:119]
	v_cvt_pk_bf16_f32 v117, v118, v119
	v_lshlrev_b64 v[118:119], 7, v[170:171]
	v_lshl_add_u64 v[118:119], v[158:159], 0, v[118:119]
	v_add_u32_e32 v170, 0x80, v170
	global_store_dwordx2 v[118:119], v[116:117], off
	s_cbranch_vccz .LBB0_1017
.LBB0_965:
	s_cmpk_lt_u32 s2, 0x7e
	s_cbranch_scc1 .Lsf_a
	s_waitcnt vmcnt(0)
.Lsf_a:
	s_waitcnt vmcnt(22)
	v_mov_b64_e32 v[194:195], v[178:179]
	v_mov_b64_e32 v[192:193], v[182:183]
	v_mov_b64_e32 v[190:191], v[184:185]
	v_mov_b64_e32 v[188:189], v[186:187]
	ds_write_b128 v204, v[4:7]
	ds_write_b128 v204, v[12:15] offset:34816
	ds_write_b128 v204, v[16:19] offset:52224
	ds_write_b128 v218, v[8:11]
	ds_write_b128 v205, v[20:23]
	ds_write_b128 v205, v[28:31] offset:34816
	ds_write_b128 v205, v[32:35] offset:52224
	ds_write_b128 v219, v[24:27]
	s_and_saveexec_b64 s[22:23], s[6:7]
	ds_write_b32 v206, v149
	s_or_b64 exec, exec, s[22:23]
	s_cmpk_lt_u32 s2, 0x7e
	s_cselect_b64 s[42:43], -1, 0
	s_cmpk_gt_u32 s2, 0x7d
	s_cselect_b64 s[40:41], -1, 0
	s_and_b64 vcc, exec, s[40:41]
	v_lshl_add_u64 v[196:197], s[48:49], 0, v[166:167]
	ds_write_b128 v207, v[48:51]
	ds_write_b128 v208, v[52:55]
	s_cbranch_vccnz .LBB0_971
	v_add_co_u32_e32 v4, vcc, 0x49aa0000, v196
	v_mov_b32_e32 v149, 0
	s_nop 0
	v_addc_co_u32_e32 v5, vcc, 0, v197, vcc
	v_add_co_u32_e32 v8, vcc, 0x49aa4000, v196
	s_nop 1
	v_addc_co_u32_e32 v9, vcc, 0, v197, vcc
	v_add_co_u32_e32 v12, vcc, 0x49aa8000, v196
	global_load_dwordx4 v[4:7], v[4:5], off offset:1024
	s_nop 0
	global_load_dwordx4 v[8:11], v[8:9], off offset:1024
	v_addc_co_u32_e32 v13, vcc, 0, v197, vcc
	v_add_co_u32_e32 v16, vcc, 0x49aac000, v196
	s_nop 1
	v_addc_co_u32_e32 v17, vcc, 0, v197, vcc
	v_add_co_u32_e32 v20, vcc, 0x49aa2000, v196
	global_load_dwordx4 v[12:15], v[12:13], off offset:1024
	s_nop 0
	global_load_dwordx4 v[16:19], v[16:17], off offset:1024
	v_addc_co_u32_e32 v21, vcc, 0, v197, vcc
	v_add_co_u32_e32 v24, vcc, 0x49aa6000, v196
	s_nop 1
	v_addc_co_u32_e32 v25, vcc, 0, v197, vcc
	v_add_co_u32_e32 v28, vcc, 0x49aaa000, v196
	global_load_dwordx4 v[20:23], v[20:21], off offset:1024
	s_nop 0
	global_load_dwordx4 v[24:27], v[24:25], off offset:1024
	v_addc_co_u32_e32 v29, vcc, 0, v197, vcc
	v_add_co_u32_e32 v32, vcc, 0x49aae000, v196
	s_nop 1
	v_addc_co_u32_e32 v33, vcc, 0, v197, vcc
	global_load_dwordx4 v[28:31], v[28:29], off offset:1024
	s_nop 0
	global_load_dwordx4 v[32:35], v[32:33], off offset:1024
	s_and_saveexec_b64 s[22:23], s[6:7]
	s_cbranch_execz .LBB0_970
	v_lshl_add_u64 v[48:49], s[48:49], 0, v[168:169]
	v_add_co_u32_e32 v48, vcc, 0x49ab0000, v48
	s_nop 1
	v_addc_co_u32_e32 v49, vcc, 0, v49, vcc
	global_load_dword v149, v[48:49], off offset:1024

.LBB0_983:
	v_mov_b32_e32 v140, s28
	s_nop 5
	v_cndmask_b32_e64 v140, v136, v140, s[12:13]
	v_cndmask_b32_e64 v140, v140, v136, s[14:15]
	v_cndmask_b32_e64 v140, v136, v140, s[8:9]
	v_mov_b32_e32 v136, s28
	v_cndmask_b32_e64 v141, 0, v137, s[14:15]
	v_cndmask_b32_e64 v142, v138, 0, s[16:17]
	v_cndmask_b32_e64 v143, v139, 0, s[18:19]
	v_cndmask_b32_e64 v136, v132, v136, s[12:13]
	v_cndmask_b32_e64 v137, v137, v141, s[8:9]
	v_cndmask_b32_e64 v139, v139, v143, s[8:9]
	v_cndmask_b32_e64 v138, v138, v142, s[8:9]
	v_cndmask_b32_e64 v141, 0, v133, s[14:15]
	v_cndmask_b32_e64 v136, v136, v132, s[14:15]
	v_cndmask_b32_e64 v142, v134, 0, s[16:17]
	v_cndmask_b32_e64 v143, v135, 0, s[18:19]
	v_cndmask_b32_e64 v141, v133, v141, s[10:11]
	v_cndmask_b32_e64 v135, v135, v143, s[10:11]
	v_cndmask_b32_e64 v142, v134, v142, s[10:11]
	v_cndmask_b32_e64 v134, v132, v136, s[10:11]
	v_cvt_pk_bf16_f32 v132, v140, v137
	v_cvt_pk_bf16_f32 v133, v138, v139
	v_cvt_pk_bf16_f32 v134, v134, v141
	v_cvt_pk_bf16_f32 v135, v142, v135
	ds_write2_b64 v222, v[132:133], v[134:135] offset1:4
	v_add_u32_e32 v132, 0, v213
	s_waitcnt lgkmcnt(0)
	s_barrier
	v_add_u32_e32 v171, 0x20000, v132
	ds_read_b128 v[132:135], v171
	ds_read_b128 v[136:139], v171 offset:64
	ds_read_b64_tr_b16 v[140:141], v214
	ds_read_b64_tr_b16 v[142:143], v214 offset:1088
	s_waitcnt lgkmcnt(3)
	v_pk_mul_f32 v[112:113], v[112:113], v[132:133]
	v_pk_mul_f32 v[114:115], v[114:115], v[134:135]
	ds_read_b128 v[132:135], v223
	ds_read_b128 v[144:147], v171 offset:128
	ds_read_b128 v[224:227], v223 offset:2304
	ds_read_b64_tr_b16 v[228:229], v214 offset:8704
	ds_read_b64_tr_b16 v[230:231], v214 offset:9792
	s_waitcnt lgkmcnt(7)
	v_pk_mul_f32 v[92:93], v[92:93], v[136:137]
	s_waitcnt lgkmcnt(4)
	v_mfma_f32_16x16x32_bf16 v[128:131], v[140:143], v[132:135], v[128:131]
	v_mul_f32_e64 v94, v94, v138
	v_mul_f32_e64 v95, v95, v139
	ds_read_b128 v[132:135], v171 offset:192
	ds_read_b128 v[136:139], v223 offset:4608
	s_waitcnt lgkmcnt(5)
	v_pk_mul_f32 v[84:85], v[84:85], v[144:145]
	s_waitcnt lgkmcnt(4)
	v_mfma_f32_16x16x32_bf16 v[124:127], v[140:143], v[224:227], v[124:127]
	ds_read_b128 v[224:227], v223 offset:6912
	ds_read_b128 v[232:235], v223 offset:4672
	v_pk_mul_f32 v[86:87], v[86:87], v[146:147]
	s_waitcnt lgkmcnt(3)
	v_pk_mul_f32 v[88:89], v[88:89], v[132:133]
	s_waitcnt lgkmcnt(2)
	v_mfma_f32_16x16x32_bf16 v[120:123], v[140:143], v[136:139], v[120:123]
	ds_read_b64_tr_b16 v[138:139], v215 offset:53312
	ds_read_b64_tr_b16 v[136:137], v215 offset:52224
	ds_read_b128 v[236:239], v223 offset:6976
	v_pk_mul_f32 v[90:91], v[90:91], v[134:135]
	s_waitcnt lgkmcnt(4)
	v_mfma_f32_16x16x32_bf16 v[116:119], v[140:143], v[224:227], v[116:119]
	ds_read_b64_tr_b16 v[226:227], v215 offset:53344
	ds_read_b64_tr_b16 v[224:225], v215 offset:52256
	ds_read_b64_tr_b16 v[240:241], v215 offset:52288
	ds_read_b64_tr_b16 v[244:245], v215 offset:52320
	ds_read_b64_tr_b16 v[242:243], v215 offset:53376
	ds_read_b64_tr_b16 v[246:247], v215 offset:53408
	ds_read_b128 v[132:135], v171 offset:320
	s_waitcnt lgkmcnt(0)
	v_pk_mul_f32 v[96:97], v[96:97], v[132:133]
	v_mfma_f32_16x16x32_bf16 v[112:115], v[136:139], v[140:143], v[112:115]
	ds_read_b128 v[136:139], v171 offset:256
	ds_read_b64_tr_b16 v[144:145], v215 offset:52352
	ds_read_b64_tr_b16 v[146:147], v215 offset:53440
	v_pk_mul_f32 v[98:99], v[98:99], v[134:135]
	v_mfma_f32_16x16x32_bf16 v[92:95], v[224:227], v[140:143], v[92:95]
	s_waitcnt lgkmcnt(2)
	v_pk_mul_f32 v[104:105], v[104:105], v[136:137]
	v_pk_mul_f32 v[106:107], v[106:107], v[138:139]
	v_mfma_f32_16x16x32_bf16 v[84:87], v[240:243], v[140:143], v[84:87]
	ds_read_b64_tr_b16 v[138:139], v215 offset:53472
	ds_read_b64_tr_b16 v[136:137], v215 offset:52384
	ds_read_b64_tr_b16 v[224:225], v215 offset:52416
	ds_read_b64_tr_b16 v[240:241], v215 offset:52448
	ds_read_b64_tr_b16 v[226:227], v215 offset:53504
	ds_read_b64_tr_b16 v[242:243], v215 offset:53536
	ds_read_b128 v[132:135], v171 offset:448
	s_waitcnt lgkmcnt(7)
	v_mfma_f32_16x16x32_bf16 v[104:107], v[144:147], v[140:143], v[104:107]
	ds_read_b128 v[144:147], v171 offset:384
	s_waitcnt lgkmcnt(0)
	v_pk_mul_f32 v[100:101], v[100:101], v[144:145]
	v_pk_mul_f32 v[102:103], v[102:103], v[146:147]
	v_mfma_f32_16x16x32_bf16 v[96:99], v[136:139], v[140:143], v[96:99]
	s_nop 0
	v_mfma_f32_16x16x32_bf16 v[136:139], v[224:227], v[140:143], v[100:103]
	v_add_u32_e32 v224, v211, v209
	s_nop 1
	v_pk_mul_f32 v[100:101], v[108:109], v[132:133]
	v_pk_mul_f32 v[102:103], v[110:111], v[134:135]
	v_mfma_f32_16x16x32_bf16 v[88:91], v[244:247], v[140:143], v[88:91]
	s_nop 0
	v_mfma_f32_16x16x32_bf16 v[132:135], v[240:243], v[140:143], v[100:103]
	s_nop 2
	ds_read_b64_tr_b16 v[100:101], v215 offset:60928
	ds_read_b64_tr_b16 v[102:103], v215 offset:62016
	ds_read_b64_tr_b16 v[110:111], v215 offset:62048
	ds_read_b64_tr_b16 v[108:109], v215 offset:60960
	ds_read_b64_tr_b16 v[140:141], v215 offset:60992
	ds_read_b64_tr_b16 v[144:145], v215 offset:61024
	ds_read_b64_tr_b16 v[142:143], v215 offset:62080
	ds_read_b64_tr_b16 v[146:147], v215 offset:62112
	s_waitcnt lgkmcnt(4)
	v_mfma_f32_16x16x32_bf16 v[108:111], v[108:111], v[228:231], v[92:95]
	s_nop 2
	ds_read_b64_tr_b16 v[92:93], v215 offset:61056
	ds_read_b64_tr_b16 v[94:95], v215 offset:62144
	v_mfma_f32_16x16x32_bf16 v[112:115], v[100:103], v[228:231], v[112:115]
	s_waitcnt lgkmcnt(3)
	v_mfma_f32_16x16x32_bf16 v[84:87], v[140:143], v[228:231], v[84:87]
	s_waitcnt lgkmcnt(2)
	v_mfma_f32_16x16x32_bf16 v[88:91], v[144:147], v[228:231], v[88:91]
	ds_read_b64_tr_b16 v[102:103], v215 offset:62176
	ds_read_b64_tr_b16 v[100:101], v215 offset:61088
	ds_read_b64_tr_b16 v[140:141], v215 offset:61120
	ds_read_b64_tr_b16 v[144:145], v215 offset:61152
	ds_read_b64_tr_b16 v[142:143], v215 offset:62208
	ds_read_b64_tr_b16 v[146:147], v215 offset:62240
	s_waitcnt lgkmcnt(6)
	v_mfma_f32_16x16x32_bf16 v[104:107], v[92:95], v[228:231], v[104:107]
	s_waitcnt lgkmcnt(4)
	v_mfma_f32_16x16x32_bf16 v[100:103], v[100:103], v[228:231], v[96:99]
	s_waitcnt lgkmcnt(1)
	v_mfma_f32_16x16x32_bf16 v[92:95], v[140:143], v[228:231], v[136:139]
	s_waitcnt lgkmcnt(0)
	v_mfma_f32_16x16x32_bf16 v[96:99], v[144:147], v[228:231], v[132:135]
	s_nop 2
	v_cvt_pk_bf16_f32 v132, v112, v113
	v_cvt_pk_bf16_f32 v133, v114, v115
	v_cvt_pk_bf16_f32 v134, v108, v109
	v_cvt_pk_bf16_f32 v135, v110, v111
	ds_write2_b64 v224, v[132:133], v[134:135] offset1:4
	v_cvt_pk_bf16_f32 v132, v84, v85
	v_cvt_pk_bf16_f32 v133, v86, v87
	v_cvt_pk_bf16_f32 v134, v88, v89
	v_cvt_pk_bf16_f32 v135, v90, v91
	ds_write2_b64 v224, v[132:133], v[134:135] offset0:8 offset1:12
	v_cvt_pk_bf16_f32 v132, v104, v105
	v_cvt_pk_bf16_f32 v133, v106, v107
	v_cvt_pk_bf16_f32 v134, v100, v101
	v_cvt_pk_bf16_f32 v135, v102, v103
	ds_write2_b64 v224, v[132:133], v[134:135] offset0:16 offset1:20
	v_cvt_pk_bf16_f32 v132, v92, v93
	v_cvt_pk_bf16_f32 v133, v94, v95
	v_cvt_pk_bf16_f32 v134, v96, v97
	v_cvt_pk_bf16_f32 v135, v98, v99
	ds_write2_b64 v224, v[132:133], v[134:135] offset0:24 offset1:28
	v_mul_f32_e32 v132, v129, v129
	v_mul_f32_e32 v133, v131, v131
	v_fmac_f32_e32 v132, v128, v128
	v_fmac_f32_e32 v133, v130, v130
	v_add_f32_e32 v132, v132, v133
	v_mov_b32_e32 v133, v132
	v_mfma_f32_16x16x32_bf16 v[120:123], v[228:231], v[232:235], v[120:123]
	s_nop 0
	v_permlane16_swap_b32_e32 v132, v133
	v_add_f32_e32 v132, v132, v133
	v_mfma_f32_16x16x32_bf16 v[116:119], v[228:231], v[236:239], v[116:119]
	v_mov_b32_e32 v133, v132
	s_nop 1
	v_permlane32_swap_b32_e32 v132, v133
	s_and_saveexec_b64 s[30:31], s[20:21]
	v_add_f32_e32 v132, v132, v133
	ds_write_b32 v217, v132
	s_or_b64 exec, exec, s[30:31]
	v_mul_f32_e32 v132, v125, v125
	v_mul_f32_e32 v133, v127, v127
	v_fmac_f32_e32 v132, v124, v124
	v_fmac_f32_e32 v133, v126, v126
	v_add_f32_e32 v132, v132, v133
	v_mov_b32_e32 v133, v132
	s_nop 1
	v_permlane16_swap_b32_e32 v132, v133
	v_add_f32_e32 v132, v132, v133
	v_mov_b32_e32 v133, v132
	s_nop 1
	v_permlane32_swap_b32_e32 v132, v133
	s_and_saveexec_b64 s[30:31], s[20:21]
	v_add_f32_e32 v132, v132, v133
	ds_write_b32 v217, v132 offset:512
	s_or_b64 exec, exec, s[30:31]
	v_mul_f32_e32 v132, v121, v121
	v_mul_f32_e32 v133, v123, v123
	v_fmac_f32_e32 v132, v120, v120
	v_fmac_f32_e32 v133, v122, v122
	v_add_f32_e32 v132, v132, v133
	v_mov_b32_e32 v133, v132
	s_nop 1
	v_permlane16_swap_b32_e32 v132, v133
	v_add_f32_e32 v132, v132, v133
	v_mov_b32_e32 v133, v132
	s_nop 1
	v_permlane32_swap_b32_e32 v132, v133
	s_and_saveexec_b64 s[30:31], s[20:21]
	v_add_f32_e32 v132, v132, v133
	ds_write_b32 v217, v132 offset:1024
	s_or_b64 exec, exec, s[30:31]
	v_mul_f32_e32 v132, v117, v117
	v_mul_f32_e32 v133, v119, v119
	v_fmac_f32_e32 v132, v116, v116
	v_fmac_f32_e32 v133, v118, v118
	v_add_f32_e32 v132, v132, v133
	v_mov_b32_e32 v133, v132
	s_nop 1
	v_permlane16_swap_b32_e32 v132, v133
	v_add_f32_e32 v132, v132, v133
	v_mov_b32_e32 v133, v132
	s_nop 1
	v_permlane32_swap_b32_e32 v132, v133
	s_and_saveexec_b64 s[30:31], s[20:21]
	v_add_f32_e32 v132, v132, v133
	ds_write_b32 v217, v132 offset:1536
	s_or_b64 exec, exec, s[30:31]
	s_waitcnt lgkmcnt(0)
	s_barrier
	ds_read_b128 v[132:135], v216
	ds_read_b128 v[136:139], v216 offset:16
	v_add_u32_e32 v154, 0xffffff90, v170
	s_waitcnt lgkmcnt(1)
	v_mov_b32_e32 v140, v132
	s_waitcnt lgkmcnt(0)
	v_mov_b32_e32 v141, v136
	v_mov_b32_e32 v136, v133
	v_pk_add_f32 v[132:133], v[140:141], v[136:137]
	v_mov_b32_e32 v136, v134
	v_mov_b32_e32 v137, v138
	v_mov_b32_e32 v138, v135
	v_pk_add_f32 v[134:135], v[136:137], v[138:139]
	s_nop 0
	v_pk_add_f32 v[132:133], v[132:133], v[134:135]
	v_lshlrev_b32_e32 v134, 16, v195
	v_add_f32_e32 v132, v132, v133
	v_fmamk_f32 v132, v132, 0x3c000000, v151
	v_rsq_f32_e32 v132, v132
	v_and_b32_e32 v135, 0xffff0000, v195
	v_mul_f32_e32 v138, 0xbfb8aa3b, v134
	v_mul_f32_e32 v139, 0xbfb8aa3b, v135
	v_pk_mul_f32 v[130:131], v[130:131], v[132:133] op_sel_hi:[1,0]
	v_pk_mul_f32 v[128:129], v[128:129], v[132:133] op_sel_hi:[1,0]
	v_pk_mul_f32 v[136:137], v[2:3], v[130:131]
	v_lshlrev_b32_e32 v130, 16, v194
	v_and_b32_e32 v131, 0xffff0000, v194
	v_mul_f32_e32 v132, 0xbfb8aa3b, v130
	v_mul_f32_e32 v133, 0xbfb8aa3b, v131
	v_exp_f32_e32 v132, v132
	v_exp_f32_e32 v133, v133
	v_exp_f32_e32 v138, v138
	v_exp_f32_e32 v139, v139
	v_add_f32_e32 v132, 1.0, v132
	v_add_f32_e32 v133, 1.0, v133
	v_rcp_f32_e32 v132, v132
	v_rcp_f32_e32 v133, v133
	v_add_f32_e32 v138, 1.0, v138
	v_add_f32_e32 v139, 1.0, v139
	v_rcp_f32_e32 v138, v138
	v_rcp_f32_e32 v139, v139
	v_pk_mul_f32 v[128:129], v[0:1], v[128:129]
	v_pk_mul_f32 v[130:131], v[132:133], v[130:131]
	v_pk_mul_f32 v[138:139], v[138:139], v[134:135]
	v_pk_mul_f32 v[128:129], v[130:131], v[128:129]
	v_pk_mul_f32 v[136:137], v[138:139], v[136:137]
	v_cvt_pk_bf16_f32 v140, v128, v129
	ds_read_b128 v[128:131], v216 offset:512
	ds_read_b128 v[132:135], v216 offset:528
	v_cvt_pk_bf16_f32 v141, v136, v137
	s_waitcnt lgkmcnt(1)
	v_mov_b32_e32 v136, v128
	s_waitcnt lgkmcnt(0)
	v_mov_b32_e32 v137, v132
	v_mov_b32_e32 v132, v129
	v_pk_add_f32 v[128:129], v[136:137], v[132:133]
	v_mov_b32_e32 v132, v130
	v_mov_b32_e32 v133, v134
	v_mov_b32_e32 v134, v131
	v_pk_add_f32 v[130:131], v[132:133], v[134:135]
	s_nop 0
	v_pk_add_f32 v[128:129], v[128:129], v[130:131]
	v_lshlrev_b64 v[130:131], 7, v[154:155]
	v_add_f32_e32 v128, v128, v129
	v_fmamk_f32 v128, v128, 0x3c000000, v151
	v_rsq_f32_e32 v128, v128
	v_lshl_add_u64 v[130:131], v[158:159], 0, v[130:131]
	global_store_dwordx2 v[130:131], v[140:141], off
	v_lshlrev_b32_e32 v130, 16, v193
	v_pk_mul_f32 v[126:127], v[126:127], v[128:129] op_sel_hi:[1,0]
	v_pk_mul_f32 v[124:125], v[124:125], v[128:129] op_sel_hi:[1,0]
	v_pk_mul_f32 v[132:133], v[2:3], v[126:127]
	v_lshlrev_b32_e32 v126, 16, v192
	v_and_b32_e32 v127, 0xffff0000, v192
	v_mul_f32_e32 v128, 0xbfb8aa3b, v126
	v_mul_f32_e32 v129, 0xbfb8aa3b, v127
	v_exp_f32_e32 v128, v128
	v_exp_f32_e32 v129, v129
	v_and_b32_e32 v131, 0xffff0000, v193
	v_mul_f32_e32 v134, 0xbfb8aa3b, v130
	v_mul_f32_e32 v135, 0xbfb8aa3b, v131
	v_exp_f32_e32 v134, v134
	v_exp_f32_e32 v135, v135
	v_add_f32_e32 v128, 1.0, v128
	v_add_f32_e32 v129, 1.0, v129
	v_rcp_f32_e32 v128, v128
	v_rcp_f32_e32 v129, v129
	v_add_f32_e32 v134, 1.0, v134
	v_add_f32_e32 v135, 1.0, v135
	v_rcp_f32_e32 v134, v134
	v_rcp_f32_e32 v135, v135
	v_pk_mul_f32 v[124:125], v[0:1], v[124:125]
	v_pk_mul_f32 v[126:127], v[128:129], v[126:127]
	v_add_u32_e32 v154, 0xffffffa0, v170
	v_pk_mul_f32 v[124:125], v[126:127], v[124:125]
	v_pk_mul_f32 v[134:135], v[134:135], v[130:131]
	v_cvt_pk_bf16_f32 v136, v124, v125
	ds_read_b128 v[124:127], v216 offset:1024
	ds_read_b128 v[128:131], v216 offset:1040
	v_pk_mul_f32 v[132:133], v[134:135], v[132:133]
	s_nop 0
	v_cvt_pk_bf16_f32 v137, v132, v133
	s_waitcnt lgkmcnt(1)
	v_mov_b32_e32 v132, v124
	s_waitcnt lgkmcnt(0)
	v_mov_b32_e32 v133, v128
	v_mov_b32_e32 v128, v125
	v_pk_add_f32 v[124:125], v[132:133], v[128:129]
	v_mov_b32_e32 v128, v126
	v_mov_b32_e32 v129, v130
	v_mov_b32_e32 v130, v127
	v_pk_add_f32 v[126:127], v[128:129], v[130:131]
	s_nop 0
	v_pk_add_f32 v[124:125], v[124:125], v[126:127]
	v_lshlrev_b64 v[126:127], 7, v[154:155]
	v_add_f32_e32 v124, v124, v125
	v_fmamk_f32 v124, v124, 0x3c000000, v151
	v_rsq_f32_e32 v124, v124
	v_lshl_add_u64 v[126:127], v[158:159], 0, v[126:127]
	global_store_dwordx2 v[126:127], v[136:137], off
	v_lshlrev_b32_e32 v126, 16, v191
	v_pk_mul_f32 v[122:123], v[122:123], v[124:125] op_sel_hi:[1,0]
	v_pk_mul_f32 v[120:121], v[120:121], v[124:125] op_sel_hi:[1,0]
	v_pk_mul_f32 v[128:129], v[2:3], v[122:123]
	v_lshlrev_b32_e32 v122, 16, v190
	v_and_b32_e32 v123, 0xffff0000, v190
	v_mul_f32_e32 v124, 0xbfb8aa3b, v122
	v_mul_f32_e32 v125, 0xbfb8aa3b, v123
	v_exp_f32_e32 v124, v124
	v_exp_f32_e32 v125, v125
	v_and_b32_e32 v127, 0xffff0000, v191
	v_mul_f32_e32 v130, 0xbfb8aa3b, v126
	v_mul_f32_e32 v131, 0xbfb8aa3b, v127
	v_exp_f32_e32 v130, v130
	v_exp_f32_e32 v131, v131
	v_add_f32_e32 v124, 1.0, v124
	v_add_f32_e32 v125, 1.0, v125
	v_rcp_f32_e32 v124, v124
	v_rcp_f32_e32 v125, v125
	v_add_f32_e32 v130, 1.0, v130
	v_add_f32_e32 v131, 1.0, v131
	v_rcp_f32_e32 v130, v130
	v_rcp_f32_e32 v131, v131
	v_pk_mul_f32 v[120:121], v[0:1], v[120:121]
	v_pk_mul_f32 v[122:123], v[124:125], v[122:123]
	v_add_u32_e32 v154, 0xffffffb0, v170
	v_pk_mul_f32 v[120:121], v[122:123], v[120:121]
	v_pk_mul_f32 v[130:131], v[130:131], v[126:127]
	v_cvt_pk_bf16_f32 v132, v120, v121
	ds_read_b128 v[120:123], v216 offset:1536
	ds_read_b128 v[124:127], v216 offset:1552
	v_pk_mul_f32 v[128:129], v[130:131], v[128:129]
	s_nop 0
	v_cvt_pk_bf16_f32 v133, v128, v129
	s_waitcnt lgkmcnt(1)
	v_mov_b32_e32 v128, v120
	s_waitcnt lgkmcnt(0)
	v_mov_b32_e32 v129, v124
	v_mov_b32_e32 v124, v121
	v_pk_add_f32 v[120:121], v[128:129], v[124:125]
	v_mov_b32_e32 v124, v122
	v_mov_b32_e32 v125, v126
	v_mov_b32_e32 v126, v123
	v_pk_add_f32 v[122:123], v[124:125], v[126:127]
	v_lshlrev_b32_e32 v124, 16, v189
	v_pk_add_f32 v[120:121], v[120:121], v[122:123]
	v_lshlrev_b64 v[122:123], 7, v[154:155]
	v_add_f32_e32 v120, v120, v121
	v_fmamk_f32 v120, v120, 0x3c000000, v151
	v_rsq_f32_e32 v120, v120
	v_lshl_add_u64 v[122:123], v[158:159], 0, v[122:123]
	global_store_dwordx2 v[122:123], v[132:133], off
	v_and_b32_e32 v125, 0xffff0000, v189
	v_pk_mul_f32 v[116:117], v[116:117], v[120:121] op_sel_hi:[1,0]
	v_pk_mul_f32 v[118:119], v[118:119], v[120:121] op_sel_hi:[1,0]
	v_lshlrev_b32_e32 v120, 16, v188
	v_and_b32_e32 v121, 0xffff0000, v188
	v_mul_f32_e32 v122, 0xbfb8aa3b, v120
	v_mul_f32_e32 v123, 0xbfb8aa3b, v121
	v_exp_f32_e32 v122, v122
	v_exp_f32_e32 v123, v123
	v_mul_f32_e32 v126, 0xbfb8aa3b, v124
	v_mul_f32_e32 v127, 0xbfb8aa3b, v125
	v_exp_f32_e32 v126, v126
	v_exp_f32_e32 v127, v127
	v_add_f32_e32 v122, 1.0, v122
	v_add_f32_e32 v123, 1.0, v123
	v_rcp_f32_e32 v122, v122
	v_rcp_f32_e32 v123, v123
	v_add_f32_e32 v126, 1.0, v126
	v_add_f32_e32 v127, 1.0, v127
	v_rcp_f32_e32 v126, v126
	v_rcp_f32_e32 v127, v127
	v_pk_mul_f32 v[116:117], v[0:1], v[116:117]
	v_pk_mul_f32 v[120:121], v[122:123], v[120:121]
	v_pk_mul_f32 v[118:119], v[2:3], v[118:119]
	v_pk_mul_f32 v[116:117], v[120:121], v[116:117]
	v_pk_mul_f32 v[120:121], v[126:127], v[124:125]
	v_subrev_u32_e32 v154, 64, v170
	v_pk_mul_f32 v[118:119], v[120:121], v[118:119]
	v_cvt_pk_bf16_f32 v116, v116, v117
	v_cvt_pk_bf16_f32 v117, v118, v119
	v_lshlrev_b64 v[118:119], 7, v[154:155]
	v_lshl_add_u64 v[118:119], v[158:159], 0, v[118:119]
	global_store_dwordx2 v[118:119], v[116:117], off
	s_waitcnt vmcnt(22)
	v_mov_b64_e32 v[194:195], v[176:177]
	v_mov_b64_e32 v[192:193], v[174:175]
	v_mov_b64_e32 v[190:191], v[172:173]
	v_mov_b64_e32 v[188:189], v[156:157]
	ds_write_b128 v204, v[36:39]
	ds_write_b128 v204, v[44:47] offset:34816
	ds_write_b128 v204, v[56:59] offset:52224
	ds_write_b128 v218, v[40:43]
	ds_write_b128 v205, v[60:63]
	ds_write_b128 v205, v[68:71] offset:34816
	ds_write_b128 v205, v[72:75] offset:52224
	ds_write_b128 v219, v[64:67]
	s_and_saveexec_b64 s[30:31], s[6:7]
	ds_write_b32 v206, v203
	s_or_b64 exec, exec, s[30:31]
	s_andn2_b64 vcc, exec, s[42:43]
	ds_write_b128 v207, v[76:79]
	ds_write_b128 v208, v[80:83]
	s_cbranch_vccnz .LBB0_997
	v_add_co_u32_e32 v36, vcc, 0x49ab0000, v196
	v_mov_b32_e32 v203, 0
	s_nop 0
	v_addc_co_u32_e32 v37, vcc, 0, v197, vcc
	v_add_co_u32_e32 v40, vcc, 0x49ab4000, v196
	s_nop 1
	v_addc_co_u32_e32 v41, vcc, 0, v197, vcc
	v_add_co_u32_e32 v44, vcc, 0x49ab8000, v196
	global_load_dwordx4 v[36:39], v[36:37], off offset:1536
	s_nop 0
	global_load_dwordx4 v[40:43], v[40:41], off offset:1536
	v_addc_co_u32_e32 v45, vcc, 0, v197, vcc
	v_add_co_u32_e32 v56, vcc, 0x49abc000, v196
	s_nop 1
	v_addc_co_u32_e32 v57, vcc, 0, v197, vcc
	v_add_co_u32_e32 v60, vcc, 0x49ab2000, v196
	global_load_dwordx4 v[44:47], v[44:45], off offset:1536
	s_nop 0
	global_load_dwordx4 v[56:59], v[56:57], off offset:1536
	v_addc_co_u32_e32 v61, vcc, 0, v197, vcc
	v_add_co_u32_e32 v64, vcc, 0x49ab6000, v196
	s_nop 1
	v_addc_co_u32_e32 v65, vcc, 0, v197, vcc
	v_add_co_u32_e32 v68, vcc, 0x49aba000, v196
	global_load_dwordx4 v[60:63], v[60:61], off offset:1536
	s_nop 0
	global_load_dwordx4 v[64:67], v[64:65], off offset:1536
	v_addc_co_u32_e32 v69, vcc, 0, v197, vcc
	v_add_co_u32_e32 v72, vcc, 0x49abe000, v196
	s_nop 1
	v_addc_co_u32_e32 v73, vcc, 0, v197, vcc
	global_load_dwordx4 v[68:71], v[68:69], off offset:1536
	s_nop 0
	global_load_dwordx4 v[72:75], v[72:73], off offset:1536
	s_and_saveexec_b64 s[30:31], s[6:7]
	s_cbranch_execz .LBB0_996
	v_lshl_add_u64 v[76:77], s[48:49], 0, v[168:169]
	v_add_co_u32_e32 v76, vcc, 0x49ac0000, v76
	s_nop 1
	v_addc_co_u32_e32 v77, vcc, 0, v77, vcc
	global_load_dword v203, v[76:77], off offset:1536
.LBB0_996:
	s_or_b64 exec, exec, s[30:31]
	v_lshl_add_u64 v[76:77], s[48:49], 0, v[164:165]
	v_add_co_u32_e32 v76, vcc, 0x34818000, v76
	v_lshl_add_u64 v[78:79], s[48:49], 0, v[162:163]
	s_nop 0
	v_addc_co_u32_e32 v77, vcc, 0, v77, vcc
	v_add_co_u32_e32 v80, vcc, 0x34818000, v78
	v_lshl_add_u64 v[116:117], s[48:49], 0, v[160:161]
	s_nop 0
	v_addc_co_u32_e32 v81, vcc, 0, v79, vcc
	v_add_co_u32_e32 v118, vcc, 0x2a818000, v116
	global_load_dwordx4 v[76:79], v[76:77], off
	s_nop 0
	global_load_dwordx4 v[80:83], v[80:81], off
	v_addc_co_u32_e32 v119, vcc, 0, v117, vcc
	v_add_co_u32_e32 v120, vcc, 0x2a81a000, v116
	s_nop 1
	v_addc_co_u32_e32 v121, vcc, 0, v117, vcc
	v_add_co_u32_e32 v122, vcc, 0x2a81c000, v116
	s_nop 1
	v_addc_co_u32_e32 v123, vcc, 0, v117, vcc
	v_add_co_u32_e32 v116, vcc, 0x2a81e000, v116
	s_nop 1
	v_addc_co_u32_e32 v117, vcc, 0, v117, vcc
	global_load_dwordx2 v[176:177], v[118:119], off
	global_load_dwordx2 v[174:175], v[120:121], off
	global_load_dwordx2 v[172:173], v[122:123], off
	global_load_dwordx2 v[156:157], v[116:117], off

.LBB0_1024:
	s_or_b64 exec, exec, s[10:11]
	v_lshlrev_b32_e32 v22, 3, v148
	v_and_b32_e32 v180, 0x78, v22
	v_add_u32_e32 v22, 0x200, v150
	s_ashr_i32 s23, s22, 31
	v_ashrrev_i32_e32 v152, 4, v150
	v_ashrrev_i32_e32 v56, 4, v22
	v_add_u32_e32 v46, s8, v54
	s_lshl_b64 s[10:11], s[22:23], 13
	v_ashrrev_i32_e32 v153, 31, v152
	v_ashrrev_i32_e32 v57, 31, v56
	v_add_u32_e32 v65, s9, v46
	v_lshl_add_u64 v[20:21], s[10:11], 0, v[152:153]
	s_lshl_b32 s9, s9, 16
	v_lshl_add_u64 v[22:23], s[10:11], 0, v[56:57]
	v_lshlrev_b64 v[20:21], 9, v[20:21]
	s_and_b32 s9, s9, 0x1000000
	v_lshlrev_b64 v[22:23], 9, v[22:23]
	v_lshl_add_u64 v[20:21], s[60:61], 0, v[20:21]
	s_and_b32 s5, s5, 0x80
	s_or_b32 s12, s9, 0x2000000
	s_mov_b32 s13, s28
	v_lshl_add_u64 v[22:23], s[60:61], 0, v[22:23]
	v_lshl_add_u64 v[20:21], v[20:21], 0, s[12:13]
	s_lshl_b32 s14, s5, 1
	s_mov_b32 s15, s28
	v_lshl_add_u64 v[22:23], v[22:23], 0, s[12:13]
	v_lshl_add_u64 v[20:21], v[20:21], 0, s[14:15]
	v_lshlrev_b32_e32 v52, 1, v180
	v_mov_b32_e32 v53, v181
	v_lshl_add_u64 v[22:23], v[22:23], 0, s[14:15]
	v_add_u32_e32 v26, 0x400, v65
	v_and_b32_e32 v55, 15, v148
	v_lshl_add_u64 v[20:21], v[20:21], 0, v[52:53]
	v_lshl_add_u64 v[24:25], v[22:23], 0, v[52:53]
	global_load_dwordx4 v[20:23], v[20:21], off
	s_nop 0
	global_load_dwordx4 v[28:31], v[24:25], off
	v_or_b32_e32 v24, s10, v55
	v_mov_b32_e32 v25, s11
	v_ashrrev_i32_e32 v26, 8, v26
	v_lshlrev_b64 v[24:25], 9, v[24:25]
	v_ashrrev_i32_e32 v27, 31, v26
	v_lshl_add_u64 v[24:25], s[60:61], 0, v[24:25]
	v_and_b32_e32 v32, 0xfc, v65
	v_lshlrev_b64 v[58:59], 24, v[26:27]
	v_lshl_add_u64 v[60:61], v[24:25], 0, v[58:59]
	v_lshlrev_b32_e32 v62, 1, v32
	v_mov_b32_e32 v63, v181
	v_lshl_add_u64 v[24:25], v[60:61], 0, v[62:63]
	v_add_co_u32_e32 v26, vcc, s2, v24
	s_mov_b32 s2, 0x8000
	s_nop 0
	v_addc_co_u32_e32 v27, vcc, 0, v25, vcc
	v_add_co_u32_e32 v32, vcc, s4, v24
	s_mov_b32 s4, 0xc000
	s_nop 0
	v_addc_co_u32_e32 v33, vcc, 0, v25, vcc
	v_add_co_u32_e32 v34, vcc, s3, v24
	s_mov_b32 s3, 0xe000
	s_nop 0
	v_addc_co_u32_e32 v35, vcc, 0, v25, vcc
	global_load_dwordx2 v[120:121], v[24:25], off
	global_load_dwordx2 v[122:123], v[26:27], off
	global_load_dwordx2 v[124:125], v[32:33], off
	global_load_dwordx2 v[126:127], v[34:35], off
	v_add_co_u32_e32 v24, vcc, s2, v36
	s_mov_b32 s2, 0xa000
	s_nop 0
	v_addc_co_u32_e32 v25, vcc, 0, v37, vcc
	v_add_co_u32_e32 v32, vcc, s2, v36
	v_mov_b32_e32 v143, v181
	s_nop 0
	v_addc_co_u32_e32 v33, vcc, 0, v37, vcc
	v_add_co_u32_e32 v38, vcc, 0xc000, v36
	global_load_dwordx4 v[24:27], v[24:25], off offset:256
	s_nop 0
	global_load_dwordx4 v[32:35], v[32:33], off offset:256
	v_addc_co_u32_e32 v39, vcc, 0, v37, vcc
	v_add_co_u32_e32 v40, vcc, 0xe000, v36
	s_nop 1
	v_addc_co_u32_e32 v41, vcc, 0, v37, vcc
	global_load_dwordx4 v[36:39], v[38:39], off offset:256
	s_nop 0
	global_load_dwordx4 v[40:43], v[40:41], off offset:256
	s_and_saveexec_b64 s[16:17], s[6:7]
	s_cbranch_execz .LBB0_1026
	v_add_co_u32_e32 v44, vcc, 0x10000, v44
	s_nop 1
	v_addc_co_u32_e32 v45, vcc, 0, v45, vcc
	global_load_dword v143, v[44:45], off offset:256

.LBB0_1027:
	s_or_b64 exec, exec, s[22:23]
	s_waitcnt lgkmcnt(0)
	s_barrier
	ds_read_b128 v[84:87], v158
	ds_read_b128 v[88:91], v158 offset:16
	s_add_i32 s33, s33, 2
	v_lshl_add_u64 v[102:103], v[102:103], 0, s[36:37]
	v_lshl_add_u64 v[104:105], v[104:105], 0, s[36:37]
	s_waitcnt lgkmcnt(1)
	v_mov_b32_e32 v92, v84
	s_waitcnt lgkmcnt(0)
	v_mov_b32_e32 v93, v88
	v_mov_b32_e32 v88, v85
	v_pk_add_f32 v[84:85], v[92:93], v[88:89]
	v_mov_b32_e32 v88, v86
	v_mov_b32_e32 v89, v90
	v_mov_b32_e32 v90, v87
	v_pk_add_f32 v[86:87], v[88:89], v[90:91]
	v_lshlrev_b32_e32 v88, 16, v139
	v_pk_add_f32 v[84:85], v[84:85], v[86:87]
	v_and_b32_e32 v89, 0xffff0000, v139
	v_add_f32_e32 v84, v84, v85
	v_fmamk_f32 v84, v84, 0x3c000000, v151
	v_rsq_f32_e32 v84, v84
	v_mul_f32_e32 v90, 0xbfb8aa3b, v88
	v_mul_f32_e32 v91, 0xbfb8aa3b, v89
	v_exp_f32_e32 v90, v90
	v_pk_mul_f32 v[80:81], v[80:81], v[84:85] op_sel_hi:[1,0]
	v_pk_mul_f32 v[82:83], v[82:83], v[84:85] op_sel_hi:[1,0]
	v_lshlrev_b32_e32 v84, 16, v138
	v_and_b32_e32 v85, 0xffff0000, v138
	v_mul_f32_e32 v86, 0xbfb8aa3b, v84
	v_mul_f32_e32 v87, 0xbfb8aa3b, v85
	v_exp_f32_e32 v86, v86
	v_exp_f32_e32 v87, v87
	v_exp_f32_e32 v91, v91
	v_add_f32_e32 v90, 1.0, v90
	v_add_f32_e32 v86, 1.0, v86
	v_add_f32_e32 v87, 1.0, v87
	v_rcp_f32_e32 v86, v86
	v_rcp_f32_e32 v87, v87
	v_add_f32_e32 v91, 1.0, v91
	v_rcp_f32_e32 v90, v90
	v_rcp_f32_e32 v91, v91
	v_pk_mul_f32 v[80:81], v[0:1], v[80:81]
	v_pk_mul_f32 v[84:85], v[86:87], v[84:85]
	v_pk_mul_f32 v[82:83], v[2:3], v[82:83]
	v_pk_mul_f32 v[80:81], v[84:85], v[80:81]
	v_lshl_add_u64 v[106:107], v[106:107], 0, s[36:37]
	v_cvt_pk_bf16_f32 v92, v80, v81
	v_pk_mul_f32 v[80:81], v[90:91], v[88:89]
	v_add_co_u32_e32 v88, vcc, s4, v134
	v_pk_mul_f32 v[80:81], v[80:81], v[82:83]
	s_nop 0
	v_addc_co_u32_e32 v89, vcc, 0, v135, vcc
	v_cvt_pk_bf16_f32 v93, v80, v81
	ds_read_b128 v[80:83], v158 offset:512
	ds_read_b128 v[84:87], v158 offset:528
	v_lshl_add_u64 v[108:109], v[108:109], 0, s[38:39]
	v_lshl_add_u64 v[110:111], v[110:111], 0, s[38:39]
	v_lshl_add_u64 v[112:113], v[112:113], 0, s[40:41]
	s_waitcnt lgkmcnt(1)
	v_mov_b32_e32 v90, v80
	s_waitcnt lgkmcnt(0)
	v_mov_b32_e32 v91, v84
	v_mov_b32_e32 v84, v81
	v_pk_add_f32 v[80:81], v[90:91], v[84:85]
	v_mov_b32_e32 v84, v82
	v_mov_b32_e32 v85, v86
	v_mov_b32_e32 v86, v83
	v_pk_add_f32 v[82:83], v[84:85], v[86:87]
	v_add_co_u32_e32 v84, vcc, s5, v134
	v_pk_add_f32 v[80:81], v[80:81], v[82:83]
	s_nop 0
	v_addc_co_u32_e32 v85, vcc, 0, v135, vcc
	v_add_f32_e32 v80, v80, v81
	v_fmamk_f32 v80, v80, 0x3c000000, v151
	v_rsq_f32_e32 v80, v80
	global_store_dwordx2 v[84:85], v[92:93], off offset:-4096
	v_lshlrev_b32_e32 v92, 16, v133
	v_and_b32_e32 v93, 0xffff0000, v133
	v_pk_mul_f32 v[78:79], v[78:79], v[80:81] op_sel_hi:[1,0]
	v_pk_mul_f32 v[76:77], v[76:77], v[80:81] op_sel_hi:[1,0]
	v_pk_mul_f32 v[86:87], v[2:3], v[78:79]
	v_lshlrev_b32_e32 v78, 16, v132
	v_and_b32_e32 v79, 0xffff0000, v132
	v_mul_f32_e32 v80, 0xbfb8aa3b, v78
	v_mul_f32_e32 v81, 0xbfb8aa3b, v79
	v_exp_f32_e32 v80, v80
	v_exp_f32_e32 v81, v81
	v_pk_mul_f32 v[90:91], v[0:1], v[76:77]
	s_andn2_b64 vcc, exec, s[42:43]
	v_add_f32_e32 v76, 1.0, v80
	v_add_f32_e32 v77, 1.0, v81
	v_mul_f32_e32 v80, 0xbfb8aa3b, v92
	v_rcp_f32_e32 v76, v76
	v_rcp_f32_e32 v77, v77
	v_exp_f32_e32 v80, v80
	v_mul_f32_e32 v81, 0xbfb8aa3b, v93
	v_exp_f32_e32 v81, v81
	v_pk_mul_f32 v[94:95], v[76:77], v[78:79]
	v_add_f32_e32 v76, 1.0, v80
	v_rcp_f32_e32 v96, v76
	v_add_f32_e32 v76, 1.0, v81
	v_rcp_f32_e32 v97, v76
	ds_read_b128 v[76:79], v158 offset:1024
	ds_read_b128 v[80:83], v158 offset:1040
	v_pk_mul_f32 v[90:91], v[94:95], v[90:91]
	v_pk_mul_f32 v[92:93], v[96:97], v[92:93]
	s_waitcnt lgkmcnt(1)
	v_mov_b32_e32 v94, v76
	s_waitcnt lgkmcnt(0)
	v_mov_b32_e32 v95, v80
	v_mov_b32_e32 v80, v77
	v_pk_add_f32 v[76:77], v[94:95], v[80:81]
	v_mov_b32_e32 v80, v78
	v_mov_b32_e32 v81, v82
	v_mov_b32_e32 v82, v79
	v_pk_add_f32 v[78:79], v[80:81], v[82:83]
	v_cvt_pk_bf16_f32 v90, v90, v91
	v_pk_add_f32 v[76:77], v[76:77], v[78:79]
	v_pk_mul_f32 v[78:79], v[92:93], v[86:87]
	v_add_f32_e32 v76, v76, v77
	v_fmamk_f32 v76, v76, 0x3c000000, v151
	v_rsq_f32_e32 v76, v76
	v_lshlrev_b32_e32 v86, 16, v131
	v_and_b32_e32 v87, 0xffff0000, v131
	v_cvt_pk_bf16_f32 v91, v78, v79
	v_pk_mul_f32 v[74:75], v[74:75], v[76:77] op_sel_hi:[1,0]
	v_pk_mul_f32 v[72:73], v[72:73], v[76:77] op_sel_hi:[1,0]
	v_pk_mul_f32 v[80:81], v[2:3], v[74:75]
	v_lshlrev_b32_e32 v74, 16, v130
	v_and_b32_e32 v75, 0xffff0000, v130
	v_mul_f32_e32 v76, 0xbfb8aa3b, v74
	v_mul_f32_e32 v77, 0xbfb8aa3b, v75
	v_exp_f32_e32 v76, v76
	v_exp_f32_e32 v77, v77
	v_pk_mul_f32 v[82:83], v[0:1], v[72:73]
	global_store_dwordx2 v[88:89], v[90:91], off offset:2048
	v_add_f32_e32 v72, 1.0, v76
	v_add_f32_e32 v73, 1.0, v77
	v_mul_f32_e32 v76, 0xbfb8aa3b, v86
	v_rcp_f32_e32 v72, v72
	v_rcp_f32_e32 v73, v73
	v_exp_f32_e32 v76, v76
	v_mul_f32_e32 v77, 0xbfb8aa3b, v87
	v_exp_f32_e32 v77, v77
	v_pk_mul_f32 v[88:89], v[72:73], v[74:75]
	v_add_f32_e32 v72, 1.0, v76
	v_rcp_f32_e32 v90, v72
	v_add_f32_e32 v72, 1.0, v77
	v_rcp_f32_e32 v91, v72
	ds_read_b128 v[72:75], v158 offset:1536
	ds_read_b128 v[76:79], v158 offset:1552
	v_pk_mul_f32 v[82:83], v[88:89], v[82:83]
	v_pk_mul_f32 v[86:87], v[90:91], v[86:87]
	s_waitcnt lgkmcnt(1)
	v_mov_b32_e32 v88, v72
	s_waitcnt lgkmcnt(0)
	v_mov_b32_e32 v89, v76
	v_mov_b32_e32 v76, v73
	v_pk_add_f32 v[72:73], v[88:89], v[76:77]
	v_mov_b32_e32 v76, v74
	v_mov_b32_e32 v77, v78
	v_mov_b32_e32 v78, v75
	v_pk_add_f32 v[74:75], v[76:77], v[78:79]
	v_cvt_pk_bf16_f32 v82, v82, v83
	v_pk_add_f32 v[72:73], v[72:73], v[74:75]
	v_pk_mul_f32 v[74:75], v[86:87], v[80:81]
	v_add_f32_e32 v72, v72, v73
	v_fmamk_f32 v72, v72, 0x3c000000, v151
	v_rsq_f32_e32 v72, v72
	v_cvt_pk_bf16_f32 v83, v74, v75
	v_lshlrev_b32_e32 v76, 16, v129
	v_and_b32_e32 v77, 0xffff0000, v129
	v_pk_mul_f32 v[68:69], v[68:69], v[72:73] op_sel_hi:[1,0]
	v_pk_mul_f32 v[70:71], v[70:71], v[72:73] op_sel_hi:[1,0]
	v_lshlrev_b32_e32 v72, 16, v128
	v_and_b32_e32 v73, 0xffff0000, v128
	v_mul_f32_e32 v74, 0xbfb8aa3b, v72
	v_mul_f32_e32 v75, 0xbfb8aa3b, v73
	v_exp_f32_e32 v74, v74
	v_exp_f32_e32 v75, v75
	v_mul_f32_e32 v78, 0xbfb8aa3b, v76
	v_mul_f32_e32 v79, 0xbfb8aa3b, v77
	v_exp_f32_e32 v78, v78
	v_exp_f32_e32 v79, v79
	v_add_f32_e32 v74, 1.0, v74
	v_add_f32_e32 v75, 1.0, v75
	v_rcp_f32_e32 v74, v74
	v_rcp_f32_e32 v75, v75
	v_add_f32_e32 v78, 1.0, v78
	v_add_f32_e32 v79, 1.0, v79
	v_rcp_f32_e32 v78, v78
	v_rcp_f32_e32 v79, v79
	v_pk_mul_f32 v[68:69], v[0:1], v[68:69]
	v_pk_mul_f32 v[72:73], v[74:75], v[72:73]
	v_pk_mul_f32 v[70:71], v[2:3], v[70:71]
	v_pk_mul_f32 v[68:69], v[72:73], v[68:69]
	v_pk_mul_f32 v[72:73], v[78:79], v[76:77]
	v_cvt_pk_bf16_f32 v68, v68, v69
	v_pk_mul_f32 v[70:71], v[72:73], v[70:71]
	v_cvt_pk_bf16_f32 v69, v70, v71
	global_store_dwordx2 v[84:85], v[82:83], off
	global_store_dwordx2 v[84:85], v[68:69], off offset:2048
	s_cbranch_vccz .LBB0_1068
.LBB0_1028:
	s_cmpk_lt_u32 s33, 0x7e
	s_cbranch_scc1 .Lsf_c
	s_waitcnt vmcnt(0)
.Lsf_c:
	s_waitcnt vmcnt(18)
	v_mov_b64_e32 v[134:135], v[120:121]
	v_mov_b64_e32 v[132:133], v[122:123]
	v_mov_b64_e32 v[130:131], v[124:125]
	v_mov_b64_e32 v[128:129], v[126:127]
	ds_write_b128 v144, v[4:7]
	ds_write_b128 v144, v[12:15] offset:18432
	ds_write_b128 v144, v[16:19] offset:27648
	ds_write_b128 v160, v[8:11]
	s_and_saveexec_b64 s[22:23], s[6:7]
	ds_write_b32 v145, v142
	s_or_b64 exec, exec, s[22:23]
	s_cmpk_lt_u32 s33, 0x7e
	s_cselect_b64 s[44:45], -1, 0
	s_cmpk_gt_u32 s33, 0x7d
	s_cselect_b64 s[42:43], -1, 0
	s_and_b64 vcc, exec, s[42:43]
	v_lshl_add_u64 v[136:137], s[48:49], 0, v[108:109]
	ds_write_b128 v146, v[20:23] offset:36864
	ds_write_b128 v147, v[28:31] offset:36864
	s_cbranch_vccnz .LBB0_1034
	v_add_co_u32_e32 v4, vcc, 0x45a10000, v136
	v_mov_b32_e32 v142, 0
	s_nop 0
	v_addc_co_u32_e32 v5, vcc, 0, v137, vcc
	v_add_co_u32_e32 v8, vcc, 0x45a12000, v136
	s_nop 1
	v_addc_co_u32_e32 v9, vcc, 0, v137, vcc
	v_add_co_u32_e32 v12, vcc, 0x45a14000, v136
	global_load_dwordx4 v[4:7], v[4:5], off offset:512
	s_nop 0
	global_load_dwordx4 v[8:11], v[8:9], off offset:512
	v_addc_co_u32_e32 v13, vcc, 0, v137, vcc
	v_add_co_u32_e32 v16, vcc, 0x45a16000, v136
	s_nop 1
	v_addc_co_u32_e32 v17, vcc, 0, v137, vcc
	global_load_dwordx4 v[12:15], v[12:13], off offset:512
	s_nop 0
	global_load_dwordx4 v[16:19], v[16:17], off offset:512
	s_and_saveexec_b64 s[22:23], s[6:7]
	s_cbranch_execz .LBB0_1033
	v_lshl_add_u64 v[20:21], s[48:49], 0, v[110:111]
	v_add_co_u32_e32 v20, vcc, 0x45a18000, v20
	s_nop 1
	v_addc_co_u32_e32 v21, vcc, 0, v21, vcc
	global_load_dword v142, v[20:21], off offset:512

.LBB0_1040:
	v_mov_b32_e32 v92, s28
	s_nop 5
	v_cndmask_b32_e64 v92, v88, v92, s[12:13]
	v_cndmask_b32_e64 v92, v92, v88, s[14:15]
	v_cndmask_b32_e64 v92, v88, v92, s[8:9]
	v_mov_b32_e32 v88, s28
	v_cndmask_b32_e64 v93, 0, v89, s[14:15]
	v_cndmask_b32_e64 v94, v90, 0, s[16:17]
	v_cndmask_b32_e64 v95, v91, 0, s[18:19]
	v_cndmask_b32_e64 v88, v84, v88, s[12:13]
	v_cndmask_b32_e64 v89, v89, v93, s[8:9]
	v_cndmask_b32_e64 v91, v91, v95, s[8:9]
	v_cndmask_b32_e64 v90, v90, v94, s[8:9]
	v_cndmask_b32_e64 v93, 0, v85, s[14:15]
	v_cndmask_b32_e64 v88, v88, v84, s[14:15]
	v_cndmask_b32_e64 v94, v86, 0, s[16:17]
	v_cndmask_b32_e64 v95, v87, 0, s[18:19]
	v_cndmask_b32_e64 v93, v85, v93, s[10:11]
	v_cndmask_b32_e64 v87, v87, v95, s[10:11]
	v_cndmask_b32_e64 v94, v86, v94, s[10:11]
	v_cndmask_b32_e64 v86, v84, v88, s[10:11]
	v_cvt_pk_bf16_f32 v84, v92, v89
	v_cvt_pk_bf16_f32 v85, v90, v91
	v_cvt_pk_bf16_f32 v86, v86, v93
	v_cvt_pk_bf16_f32 v87, v94, v87
	ds_write2_b64 v163, v[84:85], v[86:87] offset1:4
	s_waitcnt lgkmcnt(0)
	s_barrier
	ds_read_b64_tr_b16 v[84:85], v164 offset:36864
	ds_read_b64_tr_b16 v[86:87], v164 offset:37952
	v_add_u32_e32 v88, 0, v157
	v_add_u32_e32 v167, 0x14000, v88
	ds_read_b128 v[88:91], v165
	ds_read_b128 v[92:95], v167
	ds_read_b128 v[96:99], v165 offset:2304
	ds_read_b64_tr_b16 v[138:139], v164 offset:45568
	ds_read_b64_tr_b16 v[140:141], v164 offset:46656
	s_waitcnt lgkmcnt(4)
	v_mfma_f32_16x16x32_bf16 v[80:83], v[84:87], v[88:91], v[80:83]
	ds_read_b128 v[88:91], v167 offset:64
	ds_read_b128 v[168:171], v165 offset:4608
	s_waitcnt lgkmcnt(5)
	v_pk_mul_f32 v[52:53], v[52:53], v[92:93]
	s_waitcnt lgkmcnt(4)
	v_mfma_f32_16x16x32_bf16 v[76:79], v[84:87], v[96:99], v[76:79]
	v_mul_f32_e64 v54, v54, v94
	v_mul_f32_e64 v55, v55, v95
	ds_read_b128 v[92:95], v165 offset:6912
	ds_read_b128 v[96:99], v165 offset:4672
	s_waitcnt lgkmcnt(3)
	v_pk_mul_f32 v[56:57], v[56:57], v[88:89]
	s_waitcnt lgkmcnt(2)
	v_mfma_f32_16x16x32_bf16 v[72:75], v[84:87], v[168:171], v[72:75]
	ds_read_b64_tr_b16 v[170:171], v166 offset:28224
	ds_read_b64_tr_b16 v[168:169], v166 offset:27648
	ds_read_b128 v[172:175], v165 offset:6976
	v_pk_mul_f32 v[58:59], v[58:59], v[90:91]
	s_waitcnt lgkmcnt(4)
	v_mfma_f32_16x16x32_bf16 v[68:71], v[84:87], v[92:95], v[68:71]
	ds_read_b64_tr_b16 v[94:95], v166 offset:28256
	ds_read_b64_tr_b16 v[92:93], v166 offset:27680
	ds_read_b64_tr_b16 v[176:177], v166 offset:27712
	ds_read_b64_tr_b16 v[182:183], v166 offset:27744
	ds_read_b64_tr_b16 v[178:179], v166 offset:28288
	ds_read_b64_tr_b16 v[184:185], v166 offset:28320
	ds_read_b128 v[88:91], v167 offset:192
	s_waitcnt lgkmcnt(8)
	v_mfma_f32_16x16x32_bf16 v[52:55], v[168:171], v[84:87], v[52:55]
	ds_read_b128 v[168:171], v167 offset:128
	s_waitcnt lgkmcnt(0)
	v_pk_mul_f32 v[60:61], v[60:61], v[168:169]
	v_pk_mul_f32 v[62:63], v[62:63], v[170:171]
	v_mfma_f32_16x16x32_bf16 v[56:59], v[92:95], v[84:87], v[56:59]
	s_nop 0
	v_mfma_f32_16x16x32_bf16 v[92:95], v[176:179], v[84:87], v[60:63]
	s_nop 2
	v_mul_f32_e64 v60, v64, v88
	v_mul_f32_e64 v61, v65, v89
	v_pk_mul_f32 v[62:63], v[66:67], v[90:91]
	v_mfma_f32_16x16x32_bf16 v[72:75], v[138:141], v[96:99], v[72:75]
	s_nop 0
	v_mfma_f32_16x16x32_bf16 v[84:87], v[182:185], v[84:87], v[60:63]
	s_nop 2
	ds_read_b64_tr_b16 v[60:61], v166 offset:32256
	ds_read_b64_tr_b16 v[62:63], v166 offset:32832
	ds_read_b64_tr_b16 v[90:91], v166 offset:32864
	ds_read_b64_tr_b16 v[88:89], v166 offset:32288
	ds_read_b64_tr_b16 v[96:97], v166 offset:32320
	ds_read_b64_tr_b16 v[168:169], v166 offset:32352
	ds_read_b64_tr_b16 v[98:99], v166 offset:32896
	ds_read_b64_tr_b16 v[170:171], v166 offset:32928
	s_waitcnt lgkmcnt(6)
	v_mfma_f32_16x16x32_bf16 v[64:67], v[60:63], v[138:141], v[52:55]
	s_waitcnt lgkmcnt(4)
	v_mfma_f32_16x16x32_bf16 v[60:63], v[88:91], v[138:141], v[56:59]
	v_add_u32_e32 v88, v155, v149
	s_waitcnt lgkmcnt(1)
	v_mfma_f32_16x16x32_bf16 v[52:55], v[96:99], v[138:141], v[92:95]
	s_waitcnt lgkmcnt(0)
	v_mfma_f32_16x16x32_bf16 v[56:59], v[168:171], v[138:141], v[84:87]
	v_add_u32_e32 v168, 0xd000, v88
	s_nop 1
	v_cvt_pk_bf16_f32 v84, v64, v65
	v_cvt_pk_bf16_f32 v85, v66, v67
	v_cvt_pk_bf16_f32 v86, v60, v61
	v_cvt_pk_bf16_f32 v87, v62, v63
	ds_write2_b64 v168, v[84:85], v[86:87] offset0:128 offset1:132
	v_cvt_pk_bf16_f32 v84, v52, v53
	v_cvt_pk_bf16_f32 v85, v54, v55
	v_cvt_pk_bf16_f32 v86, v56, v57
	v_cvt_pk_bf16_f32 v87, v58, v59
	ds_write2_b64 v168, v[84:85], v[86:87] offset0:136 offset1:140
	v_mul_f32_e32 v84, v81, v81
	v_mul_f32_e32 v85, v83, v83
	v_fmac_f32_e32 v84, v80, v80
	v_fmac_f32_e32 v85, v82, v82
	v_add_f32_e32 v84, v84, v85
	v_mov_b32_e32 v85, v84
	v_mfma_f32_16x16x32_bf16 v[68:71], v[138:141], v[172:175], v[68:71]
	s_nop 0
	v_permlane16_swap_b32_e32 v84, v85
	v_add_f32_e32 v84, v84, v85
	v_mov_b32_e32 v85, v84
	s_nop 1
	v_permlane32_swap_b32_e32 v84, v85
	s_and_saveexec_b64 s[30:31], s[20:21]
	v_add_f32_e32 v84, v84, v85
	ds_write_b32 v159, v84
	s_or_b64 exec, exec, s[30:31]
	v_mul_f32_e32 v84, v77, v77
	v_mul_f32_e32 v85, v79, v79
	v_fmac_f32_e32 v84, v76, v76
	v_fmac_f32_e32 v85, v78, v78
	v_add_f32_e32 v84, v84, v85
	v_mov_b32_e32 v85, v84
	s_nop 1
	v_permlane16_swap_b32_e32 v84, v85
	v_add_f32_e32 v84, v84, v85
	v_mov_b32_e32 v85, v84
	s_nop 1
	v_permlane32_swap_b32_e32 v84, v85
	s_and_saveexec_b64 s[30:31], s[20:21]
	v_add_f32_e32 v84, v84, v85
	ds_write_b32 v159, v84 offset:512
	s_or_b64 exec, exec, s[30:31]
	v_mul_f32_e32 v84, v73, v73
	v_mul_f32_e32 v85, v75, v75
	v_fmac_f32_e32 v84, v72, v72
	v_fmac_f32_e32 v85, v74, v74
	v_add_f32_e32 v84, v84, v85
	v_mov_b32_e32 v85, v84
	s_nop 1
	v_permlane16_swap_b32_e32 v84, v85
	v_add_f32_e32 v84, v84, v85
	v_mov_b32_e32 v85, v84
	s_nop 1
	v_permlane32_swap_b32_e32 v84, v85
	s_and_saveexec_b64 s[30:31], s[20:21]
	v_add_f32_e32 v84, v84, v85
	ds_write_b32 v159, v84 offset:1024
	s_or_b64 exec, exec, s[30:31]
	v_mul_f32_e32 v84, v69, v69
	v_mul_f32_e32 v85, v71, v71
	v_fmac_f32_e32 v84, v68, v68
	v_fmac_f32_e32 v85, v70, v70
	v_add_f32_e32 v84, v84, v85
	v_mov_b32_e32 v85, v84
	s_nop 1
	v_permlane16_swap_b32_e32 v84, v85
	v_add_f32_e32 v84, v84, v85
	v_mov_b32_e32 v85, v84
	s_nop 1
	v_permlane32_swap_b32_e32 v84, v85
	s_and_saveexec_b64 s[30:31], s[20:21]
	v_add_f32_e32 v84, v84, v85
	ds_write_b32 v159, v84 offset:1536
	s_or_b64 exec, exec, s[30:31]
	s_waitcnt lgkmcnt(0)
	s_barrier
	ds_read_b128 v[84:87], v158
	ds_read_b128 v[88:91], v158 offset:16
	s_waitcnt lgkmcnt(1)
	v_mov_b32_e32 v92, v84
	s_waitcnt lgkmcnt(0)
	v_mov_b32_e32 v93, v88
	v_mov_b32_e32 v88, v85
	v_pk_add_f32 v[84:85], v[92:93], v[88:89]
	v_mov_b32_e32 v88, v86
	v_mov_b32_e32 v89, v90
	v_mov_b32_e32 v90, v87
	v_pk_add_f32 v[86:87], v[88:89], v[90:91]
	v_lshlrev_b32_e32 v88, 16, v135
	v_pk_add_f32 v[84:85], v[84:85], v[86:87]
	v_and_b32_e32 v89, 0xffff0000, v135
	v_add_f32_e32 v84, v84, v85
	v_fmamk_f32 v84, v84, 0x3c000000, v151
	v_rsq_f32_e32 v84, v84
	v_mul_f32_e32 v90, 0xbfb8aa3b, v88
	v_mul_f32_e32 v91, 0xbfb8aa3b, v89
	v_exp_f32_e32 v90, v90
	v_pk_mul_f32 v[80:81], v[80:81], v[84:85] op_sel_hi:[1,0]
	v_pk_mul_f32 v[82:83], v[82:83], v[84:85] op_sel_hi:[1,0]
	v_lshlrev_b32_e32 v84, 16, v134
	v_and_b32_e32 v85, 0xffff0000, v134
	v_mul_f32_e32 v86, 0xbfb8aa3b, v84
	v_mul_f32_e32 v87, 0xbfb8aa3b, v85
	v_exp_f32_e32 v86, v86
	v_exp_f32_e32 v87, v87
	v_exp_f32_e32 v91, v91
	v_add_f32_e32 v90, 1.0, v90
	v_add_f32_e32 v86, 1.0, v86
	v_add_f32_e32 v87, 1.0, v87
	v_rcp_f32_e32 v86, v86
	v_rcp_f32_e32 v87, v87
	v_add_f32_e32 v91, 1.0, v91
	v_rcp_f32_e32 v90, v90
	v_rcp_f32_e32 v91, v91
	v_pk_mul_f32 v[80:81], v[0:1], v[80:81]
	v_pk_mul_f32 v[84:85], v[86:87], v[84:85]
	v_pk_mul_f32 v[82:83], v[2:3], v[82:83]
	v_pk_mul_f32 v[80:81], v[84:85], v[80:81]
	v_lshl_add_u64 v[134:135], s[48:49], 0, v[112:113]
	v_cvt_pk_bf16_f32 v92, v80, v81
	v_pk_mul_f32 v[80:81], v[90:91], v[88:89]
	v_add_co_u32_e32 v88, vcc, s2, v134
	v_pk_mul_f32 v[80:81], v[80:81], v[82:83]
	s_nop 0
	v_addc_co_u32_e32 v89, vcc, 0, v135, vcc
	v_cvt_pk_bf16_f32 v93, v80, v81
	ds_read_b128 v[80:83], v158 offset:512
	ds_read_b128 v[84:87], v158 offset:528
	s_waitcnt lgkmcnt(1)
	v_mov_b32_e32 v90, v80
	s_waitcnt lgkmcnt(0)
	v_mov_b32_e32 v91, v84
	v_mov_b32_e32 v84, v81
	v_pk_add_f32 v[80:81], v[90:91], v[84:85]
	v_mov_b32_e32 v84, v82
	v_mov_b32_e32 v85, v86
	v_mov_b32_e32 v86, v83
	v_pk_add_f32 v[82:83], v[84:85], v[86:87]
	v_add_co_u32_e32 v84, vcc, s3, v134
	v_pk_add_f32 v[80:81], v[80:81], v[82:83]
	s_nop 0
	v_addc_co_u32_e32 v85, vcc, 0, v135, vcc
	v_add_f32_e32 v80, v80, v81
	v_fmamk_f32 v80, v80, 0x3c000000, v151
	v_rsq_f32_e32 v80, v80
	global_store_dwordx2 v[84:85], v[92:93], off offset:-4096
	v_lshlrev_b32_e32 v92, 16, v133
	v_and_b32_e32 v93, 0xffff0000, v133
	v_pk_mul_f32 v[78:79], v[78:79], v[80:81] op_sel_hi:[1,0]
	v_pk_mul_f32 v[76:77], v[76:77], v[80:81] op_sel_hi:[1,0]
	v_pk_mul_f32 v[86:87], v[2:3], v[78:79]
	v_lshlrev_b32_e32 v78, 16, v132
	v_and_b32_e32 v79, 0xffff0000, v132
	v_mul_f32_e32 v80, 0xbfb8aa3b, v78
	v_mul_f32_e32 v81, 0xbfb8aa3b, v79
	v_exp_f32_e32 v80, v80
	v_exp_f32_e32 v81, v81
	v_pk_mul_f32 v[90:91], v[0:1], v[76:77]
	v_add_f32_e32 v76, 1.0, v80
	v_add_f32_e32 v77, 1.0, v81
	v_mul_f32_e32 v80, 0xbfb8aa3b, v92
	v_rcp_f32_e32 v76, v76
	v_rcp_f32_e32 v77, v77
	v_exp_f32_e32 v80, v80
	v_mul_f32_e32 v81, 0xbfb8aa3b, v93
	v_exp_f32_e32 v81, v81
	v_pk_mul_f32 v[94:95], v[76:77], v[78:79]
	v_add_f32_e32 v76, 1.0, v80
	v_rcp_f32_e32 v96, v76
	v_add_f32_e32 v76, 1.0, v81
	v_rcp_f32_e32 v97, v76
	ds_read_b128 v[76:79], v158 offset:1024
	ds_read_b128 v[80:83], v158 offset:1040
	v_pk_mul_f32 v[90:91], v[94:95], v[90:91]
	v_pk_mul_f32 v[92:93], v[96:97], v[92:93]
	s_waitcnt lgkmcnt(1)
	v_mov_b32_e32 v94, v76
	s_waitcnt lgkmcnt(0)
	v_mov_b32_e32 v95, v80
	v_mov_b32_e32 v80, v77
	v_pk_add_f32 v[76:77], v[94:95], v[80:81]
	v_mov_b32_e32 v80, v78
	v_mov_b32_e32 v81, v82
	v_mov_b32_e32 v82, v79
	v_pk_add_f32 v[78:79], v[80:81], v[82:83]
	v_cvt_pk_bf16_f32 v90, v90, v91
	v_pk_add_f32 v[76:77], v[76:77], v[78:79]
	v_pk_mul_f32 v[78:79], v[92:93], v[86:87]
	v_add_f32_e32 v76, v76, v77
	v_fmamk_f32 v76, v76, 0x3c000000, v151
	v_rsq_f32_e32 v76, v76
	v_lshlrev_b32_e32 v86, 16, v131
	v_and_b32_e32 v87, 0xffff0000, v131
	v_cvt_pk_bf16_f32 v91, v78, v79
	v_pk_mul_f32 v[74:75], v[74:75], v[76:77] op_sel_hi:[1,0]
	v_pk_mul_f32 v[72:73], v[72:73], v[76:77] op_sel_hi:[1,0]
	v_pk_mul_f32 v[80:81], v[2:3], v[74:75]
	v_lshlrev_b32_e32 v74, 16, v130
	v_and_b32_e32 v75, 0xffff0000, v130
	v_mul_f32_e32 v76, 0xbfb8aa3b, v74
	v_mul_f32_e32 v77, 0xbfb8aa3b, v75
	v_exp_f32_e32 v76, v76
	v_exp_f32_e32 v77, v77
	v_pk_mul_f32 v[82:83], v[0:1], v[72:73]
	global_store_dwordx2 v[88:89], v[90:91], off offset:2048
	v_add_f32_e32 v72, 1.0, v76
	v_add_f32_e32 v73, 1.0, v77
	v_mul_f32_e32 v76, 0xbfb8aa3b, v86
	v_rcp_f32_e32 v72, v72
	v_rcp_f32_e32 v73, v73
	v_exp_f32_e32 v76, v76
	v_mul_f32_e32 v77, 0xbfb8aa3b, v87
	v_exp_f32_e32 v77, v77
	v_pk_mul_f32 v[88:89], v[72:73], v[74:75]
	v_add_f32_e32 v72, 1.0, v76
	v_rcp_f32_e32 v90, v72
	v_add_f32_e32 v72, 1.0, v77
	v_rcp_f32_e32 v91, v72
	ds_read_b128 v[72:75], v158 offset:1536
	ds_read_b128 v[76:79], v158 offset:1552
	v_pk_mul_f32 v[82:83], v[88:89], v[82:83]
	v_pk_mul_f32 v[86:87], v[90:91], v[86:87]
	s_waitcnt lgkmcnt(1)
	v_mov_b32_e32 v88, v72
	s_waitcnt lgkmcnt(0)
	v_mov_b32_e32 v89, v76
	v_mov_b32_e32 v76, v73
	v_pk_add_f32 v[72:73], v[88:89], v[76:77]
	v_mov_b32_e32 v76, v74
	v_mov_b32_e32 v77, v78
	v_mov_b32_e32 v78, v75
	v_pk_add_f32 v[74:75], v[76:77], v[78:79]
	v_cvt_pk_bf16_f32 v82, v82, v83
	v_pk_add_f32 v[72:73], v[72:73], v[74:75]
	v_pk_mul_f32 v[74:75], v[86:87], v[80:81]
	v_add_f32_e32 v72, v72, v73
	v_fmamk_f32 v72, v72, 0x3c000000, v151
	v_rsq_f32_e32 v72, v72
	v_cvt_pk_bf16_f32 v83, v74, v75
	v_lshlrev_b32_e32 v76, 16, v129
	v_and_b32_e32 v77, 0xffff0000, v129
	v_pk_mul_f32 v[68:69], v[68:69], v[72:73] op_sel_hi:[1,0]
	v_pk_mul_f32 v[70:71], v[70:71], v[72:73] op_sel_hi:[1,0]
	v_lshlrev_b32_e32 v72, 16, v128
	v_and_b32_e32 v73, 0xffff0000, v128
	v_mul_f32_e32 v74, 0xbfb8aa3b, v72
	v_mul_f32_e32 v75, 0xbfb8aa3b, v73
	v_exp_f32_e32 v74, v74
	v_exp_f32_e32 v75, v75
	v_mul_f32_e32 v78, 0xbfb8aa3b, v76
	v_mul_f32_e32 v79, 0xbfb8aa3b, v77
	v_exp_f32_e32 v78, v78
	v_exp_f32_e32 v79, v79
	v_add_f32_e32 v74, 1.0, v74
	v_add_f32_e32 v75, 1.0, v75
	v_rcp_f32_e32 v74, v74
	v_rcp_f32_e32 v75, v75
	v_add_f32_e32 v78, 1.0, v78
	v_add_f32_e32 v79, 1.0, v79
	v_rcp_f32_e32 v78, v78
	v_rcp_f32_e32 v79, v79
	v_pk_mul_f32 v[68:69], v[0:1], v[68:69]
	v_pk_mul_f32 v[72:73], v[74:75], v[72:73]
	v_pk_mul_f32 v[70:71], v[2:3], v[70:71]
	v_pk_mul_f32 v[68:69], v[72:73], v[68:69]
	v_pk_mul_f32 v[72:73], v[78:79], v[76:77]
	v_cvt_pk_bf16_f32 v68, v68, v69
	v_pk_mul_f32 v[70:71], v[72:73], v[70:71]
	global_store_dwordx2 v[84:85], v[82:83], off
	v_cvt_pk_bf16_f32 v69, v70, v71
	global_store_dwordx2 v[84:85], v[68:69], off offset:2048
	s_waitcnt vmcnt(18)
	v_mov_b64_e32 v[138:139], v[118:119]
	v_mov_b64_e32 v[132:133], v[116:117]
	v_mov_b64_e32 v[130:131], v[114:115]
	v_mov_b64_e32 v[128:129], v[100:101]
	ds_write_b128 v144, v[24:27]
	ds_write_b128 v144, v[36:39] offset:18432
	ds_write_b128 v144, v[40:43] offset:27648
	ds_write_b128 v160, v[32:35]
	s_and_saveexec_b64 s[30:31], s[6:7]
	ds_write_b32 v145, v143
	s_or_b64 exec, exec, s[30:31]
	s_andn2_b64 vcc, exec, s[44:45]
	ds_write_b128 v146, v[44:47] offset:36864
	ds_write_b128 v147, v[48:51] offset:36864
	s_cbranch_vccnz .LBB0_1054
	v_add_co_u32_e32 v24, vcc, 0x45a18000, v136
	v_mov_b32_e32 v143, 0
	s_nop 0
	v_addc_co_u32_e32 v25, vcc, 0, v137, vcc
	v_add_co_u32_e32 v32, vcc, 0x45a1a000, v136
	s_nop 1
	v_addc_co_u32_e32 v33, vcc, 0, v137, vcc
	v_add_co_u32_e32 v36, vcc, 0x45a1c000, v136
	global_load_dwordx4 v[24:27], v[24:25], off offset:768
	s_nop 0
	global_load_dwordx4 v[32:35], v[32:33], off offset:768
	v_addc_co_u32_e32 v37, vcc, 0, v137, vcc
	v_add_co_u32_e32 v40, vcc, 0x45a1e000, v136
	s_nop 1
	v_addc_co_u32_e32 v41, vcc, 0, v137, vcc
	global_load_dwordx4 v[36:39], v[36:37], off offset:768
	s_nop 0
	global_load_dwordx4 v[40:43], v[40:41], off offset:768
	s_and_saveexec_b64 s[30:31], s[6:7]
	s_cbranch_execz .LBB0_1053
	v_lshl_add_u64 v[44:45], s[48:49], 0, v[110:111]
	v_add_co_u32_e32 v44, vcc, 0x45a20000, v44
	s_nop 1
	v_addc_co_u32_e32 v45, vcc, 0, v45, vcc
	global_load_dword v143, v[44:45], off offset:768
.LBB0_1053:
	s_or_b64 exec, exec, s[30:31]
	v_lshl_add_u64 v[44:45], s[48:49], 0, v[106:107]
	v_add_co_u32_e32 v44, vcc, 0x2c818000, v44
	v_lshl_add_u64 v[46:47], s[48:49], 0, v[104:105]
	s_nop 0
	v_addc_co_u32_e32 v45, vcc, 0, v45, vcc
	v_add_co_u32_e32 v48, vcc, 0x2c818000, v46
	v_lshl_add_u64 v[68:69], s[48:49], 0, v[102:103]
	s_nop 0
	v_addc_co_u32_e32 v49, vcc, 0, v47, vcc
	v_add_co_u32_e32 v70, vcc, 0x2a818000, v68
	global_load_dwordx4 v[44:47], v[44:45], off
	s_nop 0
	global_load_dwordx4 v[48:51], v[48:49], off
	v_addc_co_u32_e32 v71, vcc, 0, v69, vcc
	v_add_co_u32_e32 v72, vcc, 0x2a81a000, v68
	s_nop 1
	v_addc_co_u32_e32 v73, vcc, 0, v69, vcc
	v_add_co_u32_e32 v74, vcc, 0x2a81c000, v68
	s_nop 1
	v_addc_co_u32_e32 v75, vcc, 0, v69, vcc
	v_add_co_u32_e32 v68, vcc, 0x2a81e000, v68
	s_nop 1
	v_addc_co_u32_e32 v69, vcc, 0, v69, vcc
	global_load_dwordx2 v[118:119], v[70:71], off
	global_load_dwordx2 v[116:117], v[72:73], off
	global_load_dwordx2 v[114:115], v[74:75], off
	global_load_dwordx2 v[100:101], v[68:69], off

.LBB0_2221:
	s_or_b64 exec, exec, s[10:11]
	v_add_u32_e32 v101, 0x200, v150
	v_ashrrev_i32_e32 v152, 4, v150
	v_ashrrev_i32_e32 v94, 4, v101
	s_lshl_b32 s24, s2, 13
	s_mov_b32 s25, s28
	v_ashrrev_i32_e32 v153, 31, v152
	v_lshlrev_b32_e32 v38, 3, v148
	v_ashrrev_i32_e32 v95, 31, v94
	v_lshl_add_u64 v[36:37], s[24:25], 0, v[152:153]
	s_lshl_b32 s2, s75, 23
	v_and_b32_e32 v180, 0x78, v38
	v_lshl_add_u64 v[38:39], s[24:25], 0, v[94:95]
	v_lshlrev_b64 v[88:89], 9, v[36:37]
	s_and_b32 s2, s2, 0x1000000
	v_lshlrev_b64 v[90:91], 9, v[38:39]
	v_add_u32_e32 v78, s8, v84
	v_lshl_add_u64 v[36:37], s[60:61], 0, v[88:89]
	s_and_b32 s9, s9, 0x80
	s_or_b32 s10, s2, 0xa000000
	s_mov_b32 s11, s28
	v_lshl_add_u64 v[38:39], s[60:61], 0, v[90:91]
	v_add_u32_e32 v85, s12, v78
	v_lshl_add_u64 v[36:37], v[36:37], 0, s[10:11]
	s_lshl_b32 s12, s9, 1
	s_mov_b32 s13, s28
	v_lshl_add_u64 v[38:39], v[38:39], 0, s[10:11]
	v_lshl_add_u64 v[36:37], v[36:37], 0, s[12:13]
	v_lshlrev_b32_e32 v154, 1, v180
	v_mov_b32_e32 v155, v181
	v_lshl_add_u64 v[38:39], v[38:39], 0, s[12:13]
	v_add_u32_e32 v40, 0xc00, v85
	v_and_b32_e32 v86, 15, v148
	v_lshl_add_u64 v[36:37], v[36:37], 0, v[154:155]
	v_lshl_add_u64 v[38:39], v[38:39], 0, v[154:155]
	global_load_dwordx4 v[48:51], v[36:37], off
	global_load_dwordx4 v[52:55], v[38:39], off
	v_or_b32_e32 v36, s24, v86
	v_mov_b32_e32 v37, v181
	v_ashrrev_i32_e32 v38, 8, v40
	v_lshlrev_b64 v[36:37], 9, v[36:37]
	v_ashrrev_i32_e32 v39, 31, v38
	v_lshl_add_u64 v[36:37], s[60:61], 0, v[36:37]
	v_and_b32_e32 v40, 0xfc, v85
	v_lshlrev_b64 v[92:93], 24, v[38:39]
	v_lshl_add_u64 v[96:97], v[36:37], 0, v[92:93]
	v_lshlrev_b32_e32 v98, 1, v40
	v_mov_b32_e32 v99, v181
	v_lshl_add_u64 v[36:37], v[96:97], 0, v[98:99]
	v_add_co_u32_e32 v38, vcc, s5, v36
	v_mov_b32_e32 v87, v181
	s_nop 0
	v_addc_co_u32_e32 v39, vcc, 0, v37, vcc
	v_add_co_u32_e32 v40, vcc, s3, v36
	s_mov_b32 s3, 0x10000
	s_nop 0
	v_addc_co_u32_e32 v41, vcc, 0, v37, vcc
	v_add_co_u32_e32 v42, vcc, s4, v36
	v_mov_b32_e32 v203, v181
	s_nop 0
	v_addc_co_u32_e32 v43, vcc, 0, v37, vcc
	global_load_dwordx2 v[178:179], v[36:37], off
	global_load_dwordx2 v[182:183], v[38:39], off
	global_load_dwordx2 v[184:185], v[40:41], off
	global_load_dwordx2 v[186:187], v[42:43], off
	v_add_co_u32_e32 v36, vcc, s3, v68
	s_mov_b32 s3, 0x14000
	s_nop 0
	v_addc_co_u32_e32 v37, vcc, 0, v69, vcc
	v_add_co_u32_e32 v40, vcc, s3, v68
	s_mov_b32 s3, 0x18000
	s_nop 0
	v_addc_co_u32_e32 v41, vcc, 0, v69, vcc
	v_add_co_u32_e32 v44, vcc, s3, v68
	s_mov_b32 s3, 0x1c000
	s_nop 0
	v_addc_co_u32_e32 v45, vcc, 0, v69, vcc
	v_add_co_u32_e32 v56, vcc, s3, v68
	s_mov_b32 s3, 0x12000
	s_nop 0
	v_addc_co_u32_e32 v57, vcc, 0, v69, vcc
	v_add_co_u32_e32 v60, vcc, s3, v68
	s_mov_b32 s3, 0x16000
	s_nop 0
	v_addc_co_u32_e32 v61, vcc, 0, v69, vcc
	v_add_co_u32_e32 v64, vcc, s3, v68
	global_load_dwordx4 v[36:39], v[36:37], off offset:512
	s_nop 0
	global_load_dwordx4 v[40:43], v[40:41], off offset:512
	v_addc_co_u32_e32 v65, vcc, 0, v69, vcc
	v_add_co_u32_e32 v70, vcc, 0x1a000, v68
	global_load_dwordx4 v[44:47], v[44:45], off offset:512
	s_nop 0
	global_load_dwordx4 v[56:59], v[56:57], off offset:512
	v_addc_co_u32_e32 v71, vcc, 0, v69, vcc
	v_add_co_u32_e32 v72, vcc, 0x1e000, v68
	global_load_dwordx4 v[60:63], v[60:61], off offset:512
	s_nop 0
	global_load_dwordx4 v[64:67], v[64:65], off offset:512
	v_addc_co_u32_e32 v73, vcc, 0, v69, vcc
	global_load_dwordx4 v[68:71], v[70:71], off offset:512
	s_nop 0
	global_load_dwordx4 v[72:75], v[72:73], off offset:512
	s_movk_i32 s3, 0x200
	s_and_saveexec_b64 s[14:15], s[6:7]
	s_cbranch_execz .LBB0_2223
	v_add_co_u32_e32 v76, vcc, 0x20000, v76
	s_nop 1
	v_addc_co_u32_e32 v77, vcc, 0, v77, vcc
	global_load_dword v203, v[76:77], off offset:512
